# A+Q+P2 + swiglu epilogue v_pk_fma_f32 (broadcast form) split into scalar v_fma_f32 pairs
# baseline (speedup 1.0000x reference)
; __device__ __forceinline__ unsigned cvt_pk_bf16(float lo, float hi) { unsigned r; asm volatile("v_cvt_pk_bf16_f32 %0, %1, %2" : "=v"(r) : "v"(lo), "v"(hi)); return r; }
; __device__ __forceinline__ float silu_mul(float a, float b) { return a * b * __builtin_amdgcn_rcpf(1.0f + __builtin_amdgcn_exp2f(-a * LOG2E)); }
; __device__ __forceinline__ float row_rstd(const float* ss, int row) { return 1.0f / sqrtf(ss[row] * (1.0f / DM) + 1e-6f); }
;     __device__ __forceinline__ void operator()(const f32x4 (&acc)[2][2][4][2], const Unit& u, int wr, int wc, int fr, int fq) const {
;         const int row0 = u.pm * BM + wr * 64 + fr, col0 = u.pn * HALF + wc * 32 + 8 * fq;
;         const int s = (u.pm < ML / BM) ? (u.pm >> 5) : 4;
;         const float* bp = bias + (size_t)s * BIAS_N + u.pn * BM + wc * 32 + 8 * fq;
;         const f32x4 ba0 = *(const f32x4*)bp, ba1 = *(const f32x4*)(bp + 4), bb0 = *(const f32x4*)(bp + HALF), bb1 = *(const f32x4*)(bp + HALF + 4);
;         const int lane = fq * 16 + fr;
;         const float rsl0 = row_rstd(ss, u.pm * BM + wr * 64 + lane), rsl1 = row_rstd(ss, u.pm * BM + HALF + wr * 64 + lane);
; #pragma unroll
;         for (int ai = 0; ai < 2; ++ai)
; #pragma unroll
;             for (int m = 0; m < 4; ++m) { const int row = row0 + ai * HALF + m * 16; const float rs = __shfl(ai ? rsl1 : rsl0, m * 16 + fr); bf16_t* rowp = O + (size_t)row * DFF + col0;
;                 const f32x4 a0 = acc[ai][0][m][0] * rs + ba0, a1 = acc[ai][0][m][1] * rs + ba1, b0 = acc[ai][1][m][0] * rs + bb0, b1 = acc[ai][1][m][1] * rs + bb1;
;                 u32x4 w; w.x = cvt_pk_bf16(silu_mul(a0[0], b0[0]), silu_mul(a0[1], b0[1])); w.y = cvt_pk_bf16(silu_mul(a0[2], b0[2]), silu_mul(a0[3], b0[3]));
;                 w.z = cvt_pk_bf16(silu_mul(a1[0], b1[0]), silu_mul(a1[1], b1[1])); w.w = cvt_pk_bf16(silu_mul(a1[2], b1[2]), silu_mul(a1[3], b1[3]));
;                 *(u32x4*)rowp = w; }
.LBB0_193:
	s_lshl_b32 s2, s2, 8
	s_add_i32 s12, s2, s54
	s_lshl_b64 s[2:3], s[16:17], 2
	s_add_u32 s13, s68, s2
	s_addc_u32 s14, s69, s3
	s_lshl_b32 s2, s0, 8
	s_ashr_i32 s3, s2, 31
	s_lshl_b64 s[2:3], s[2:3], 2
	v_lshl_or_b32 v164, s0, 7, v173
	s_add_u32 s0, s13, s2
	s_addc_u32 s3, s14, s3
	v_or_b32_e32 v162, s12, v171
	s_add_u32 s2, s0, s60
	v_ashrrev_i32_e32 v163, 31, v162
	s_addc_u32 s3, s3, 0
	v_lshl_add_u64 v[162:163], v[162:163], 2, s[8:9]
	v_mov_b32_e32 v74, v234
	v_mov_b32_e32 v75, v235
	v_mov_b32_e32 v76, v236
	v_mov_b32_e32 v77, v237
	v_mov_b32_e32 v78, v238
	v_mov_b32_e32 v79, v239
	v_mov_b32_e32 v80, v240
	v_mov_b32_e32 v81, v241
	v_mov_b32_e32 v66, v242
	v_mov_b32_e32 v67, v243
	v_mov_b32_e32 v68, v244
	v_mov_b32_e32 v69, v245
	v_mov_b32_e32 v70, v246
	v_mov_b32_e32 v71, v247
	v_mov_b32_e32 v72, v248
	v_mov_b32_e32 v73, v249
	v_or_b32_e32 v181, s12, v169
	v_mov_b32_e32 v162, v250
	s_waitcnt vmcnt(0)
	v_fmamk_f32 v162, v162, 0x3a000000, v178
	v_cmp_gt_f32_e32 vcc, s61, v162
	v_mul_f32_e32 v163, 0x4f800000, v162
	s_nop 0
	v_cndmask_b32_e32 v162, v162, v163, vcc
	v_sqrt_f32_e32 v163, v162
	s_nop 0
	v_add_u32_e32 v165, -1, v163
	v_fma_f32 v166, -v165, v163, v162
	v_cmp_ge_f32_e64 s[2:3], 0, v166
	v_add_u32_e32 v166, 1, v163
	s_nop 0
	v_cndmask_b32_e64 v165, v163, v165, s[2:3]
	v_fma_f32 v163, -v166, v163, v162
	v_cmp_lt_f32_e64 s[2:3], 0, v163
	s_nop 1
	v_cndmask_b32_e64 v163, v165, v166, s[2:3]
	v_mul_f32_e32 v165, 0x37800000, v163
	v_cndmask_b32_e32 v163, v163, v165, vcc
	v_cmp_class_f32_e32 vcc, v162, v179
	s_nop 1
	v_cndmask_b32_e32 v166, v163, v162, vcc
	v_add_u32_e32 v162, s12, v172
	v_ashrrev_i32_e32 v163, 31, v162
	v_lshl_add_u64 v[162:163], v[162:163], 2, s[8:9]
	v_mov_b32_e32 v162, v251
	v_fmamk_f32 v162, v162, 0x3a000000, v178
	v_cmp_gt_f32_e32 vcc, s61, v162
	v_mul_f32_e32 v163, 0x4f800000, v162
	s_nop 0
	v_cndmask_b32_e32 v162, v162, v163, vcc
	v_sqrt_f32_e32 v163, v162
	s_nop 0
	v_add_u32_e32 v165, -1, v163
	v_fma_f32 v167, -v165, v163, v162
	v_cmp_ge_f32_e64 s[2:3], 0, v167
	v_add_u32_e32 v167, 1, v163
	s_nop 0
	v_cndmask_b32_e64 v165, v163, v165, s[2:3]
	v_fma_f32 v163, -v167, v163, v162
	v_cmp_lt_f32_e64 s[2:3], 0, v163
	s_nop 1
	v_cndmask_b32_e64 v163, v165, v167, s[2:3]
	v_mul_f32_e32 v165, 0x37800000, v163
	v_cndmask_b32_e32 v163, v163, v165, vcc
	v_cmp_class_f32_e32 vcc, v162, v179
	v_ashrrev_i32_e32 v165, 31, v164
	v_lshlrev_b64 v[164:165], 1, v[164:165]
	v_cndmask_b32_e32 v182, v163, v162, vcc
	v_div_scale_f32 v162, s[2:3], v166, v166, 1.0
	v_rcp_f32_e32 v163, v162
	s_nop 0
	v_fma_f32 v167, -v162, v163, 1.0
	v_fmac_f32_e32 v163, v167, v163
	v_div_scale_f32 v167, vcc, 1.0, v166, 1.0
	v_mul_f32_e32 v168, v167, v163
	v_fma_f32 v183, -v162, v168, v167
	v_fmac_f32_e32 v168, v183, v163
	v_fma_f32 v162, -v162, v168, v167
	v_div_fmas_f32 v162, v162, v163, v168
	v_div_fixup_f32 v183, v162, v166, 1.0
	ds_bpermute_b32 v168, v180, v183
	v_mov_b64_e32 v[162:163], s[96:97]
	v_mad_i64_i32 v[166:167], s[2:3], v181, s59, v[162:163]
	v_lshl_add_u64 v[166:167], v[166:167], 0, v[164:165]
	s_waitcnt lgkmcnt(0)
	v_fma_f32 v142, v142, v168, v78
	v_fma_f32 v143, v143, v168, v79
	v_fma_f32 v134, v134, v168, v70
	v_fma_f32 v135, v135, v168, v71
	v_fma_f32 v184, v132, v168, v68
	v_fma_f32 v185, v133, v168, v69
	v_fma_f32 v132, v130, v168, v66
	v_fma_f32 v133, v131, v168, v67
	v_mul_f32_e32 v131, 0xbfb8aa3b, v142
	v_mul_f32_e32 v130, v142, v134
	v_exp_f32_e32 v131, v131
	v_mul_f32_e32 v134, 0xbfb8aa3b, v143
	v_exp_f32_e32 v134, v134
	v_fma_f32 v144, v144, v168, v80
	v_fma_f32 v145, v145, v168, v81
	v_add_f32_e32 v131, 1.0, v131
	v_rcp_f32_e32 v131, v131
	v_add_f32_e32 v134, 1.0, v134
	v_rcp_f32_e32 v134, v134
	v_fma_f32 v136, v136, v168, v72
	v_fma_f32 v137, v137, v168, v73
	v_mul_f32_e32 v130, v130, v131
	v_mul_f32_e32 v131, v143, v135
	v_mul_f32_e32 v131, v131, v134
	v_mul_f32_e32 v134, 0xbfb8aa3b, v144
	v_exp_f32_e32 v134, v134
	v_mul_f32_e32 v135, 0xbfb8aa3b, v145
	v_exp_f32_e32 v135, v135
	v_cvt_pk_bf16_f32 v130, v130, v131
	v_add_f32_e32 v134, 1.0, v134
	v_rcp_f32_e32 v134, v134
	v_add_f32_e32 v135, 1.0, v135
	v_rcp_f32_e32 v135, v135
	v_mul_f32_e32 v131, v144, v136
	v_mul_f32_e32 v131, v131, v134
	v_mul_f32_e32 v134, v145, v137
	v_fma_f32 v138, v138, v168, v74
	v_fma_f32 v139, v139, v168, v75
	v_mul_f32_e32 v134, v134, v135
	v_cvt_pk_bf16_f32 v131, v131, v134
	v_mul_f32_e32 v134, 0xbfb8aa3b, v138
	v_exp_f32_e32 v134, v134
	v_mul_f32_e32 v132, v138, v132
	v_fma_f32 v140, v140, v168, v76
	v_fma_f32 v141, v141, v168, v77
	v_mul_f32_e32 v133, v139, v133
	v_add_f32_e32 v134, 1.0, v134
	v_rcp_f32_e32 v134, v134
	v_mul_f32_e32 v135, 0xbfb8aa3b, v141
	v_exp_f32_e32 v135, v135
	v_mul_f32_e32 v132, v132, v134
	v_mul_f32_e32 v134, 0xbfb8aa3b, v139
	v_exp_f32_e32 v134, v134
	v_add_f32_e32 v135, 1.0, v135
	v_rcp_f32_e32 v135, v135
	v_add_f32_e32 v134, 1.0, v134
	v_rcp_f32_e32 v134, v134
	s_nop 0
	v_mul_f32_e32 v133, v133, v134
	v_mul_f32_e32 v134, 0xbfb8aa3b, v140
	v_exp_f32_e32 v134, v134
	v_cvt_pk_bf16_f32 v132, v132, v133
	v_mul_f32_e32 v133, v140, v184
	v_add_f32_e32 v134, 1.0, v134
	v_rcp_f32_e32 v134, v134
	s_nop 0
	v_mul_f32_e32 v133, v133, v134
	v_mul_f32_e32 v134, v141, v185
	v_mul_f32_e32 v134, v134, v135
	v_cvt_pk_bf16_f32 v133, v133, v134
	global_store_dwordx4 v[166:167], v[130:133], off
	ds_bpermute_b32 v130, v180, v183 offset:64
	s_nop 0
	v_or_b32_e32 v131, 16, v181
	v_mad_i64_i32 v[132:133], s[2:3], v131, s59, v[162:163]
	s_waitcnt lgkmcnt(0)
; __device__ __forceinline__ unsigned cvt_pk_bf16(float lo, float hi) { unsigned r; asm volatile("v_cvt_pk_bf16_f32 %0, %1, %2" : "=v"(r) : "v"(lo), "v"(hi)); return r; }
; __device__ __forceinline__ float silu_mul(float a, float b) { return a * b * __builtin_amdgcn_rcpf(1.0f + __builtin_amdgcn_exp2f(-a * LOG2E)); }
;     __device__ __forceinline__ void operator()(const f32x4 (&acc)[2][2][4][2], const Unit& u, int wr, int wc, int fr, int fq) const {
;     ...
;             for (int m = 0; m < 4; ++m) { const int row = row0 + ai * HALF + m * 16; const float rs = __shfl(ai ? rsl1 : rsl0, m * 16 + fr); bf16_t* rowp = O + (size_t)row * DFF + col0;
;                 const f32x4 a0 = acc[ai][0][m][0] * rs + ba0, a1 = acc[ai][0][m][1] * rs + ba1, b0 = acc[ai][1][m][0] * rs + bb0, b1 = acc[ai][1][m][1] * rs + bb1;
;                 u32x4 w; w.x = cvt_pk_bf16(silu_mul(a0[0], b0[0]), silu_mul(a0[1], b0[1])); w.y = cvt_pk_bf16(silu_mul(a0[2], b0[2]), silu_mul(a0[3], b0[3]));
;                 w.z = cvt_pk_bf16(silu_mul(a1[0], b1[0]), silu_mul(a1[1], b1[1])); w.w = cvt_pk_bf16(silu_mul(a1[2], b1[2]), silu_mul(a1[3], b1[3]));
;                 *(u32x4*)rowp = w; }
	v_fma_f32 v126, v126, v130, v78
	v_fma_f32 v127, v127, v130, v79
	v_fma_f32 v118, v118, v130, v70
	v_fma_f32 v119, v119, v130, v71
	v_fma_f32 v134, v116, v130, v68
	v_fma_f32 v135, v117, v130, v69
	v_fma_f32 v116, v114, v130, v66
	v_fma_f32 v117, v115, v130, v67
	v_mul_f32_e32 v115, 0xbfb8aa3b, v126
	v_mul_f32_e32 v114, v126, v118
	v_exp_f32_e32 v115, v115
	v_mul_f32_e32 v118, 0xbfb8aa3b, v127
	v_exp_f32_e32 v118, v118
	v_fma_f32 v128, v128, v130, v80
	v_fma_f32 v129, v129, v130, v81
	v_add_f32_e32 v115, 1.0, v115
	v_rcp_f32_e32 v115, v115
	v_add_f32_e32 v118, 1.0, v118
	v_rcp_f32_e32 v118, v118
	v_fma_f32 v120, v120, v130, v72
	v_fma_f32 v121, v121, v130, v73
	v_mul_f32_e32 v114, v114, v115
	v_mul_f32_e32 v115, v127, v119
	v_mul_f32_e32 v115, v115, v118
	v_mul_f32_e32 v118, 0xbfb8aa3b, v128
	v_exp_f32_e32 v118, v118
	v_mul_f32_e32 v119, 0xbfb8aa3b, v129
	v_exp_f32_e32 v119, v119
	v_cvt_pk_bf16_f32 v114, v114, v115
	v_add_f32_e32 v118, 1.0, v118
	v_rcp_f32_e32 v118, v118
	v_add_f32_e32 v119, 1.0, v119
	v_rcp_f32_e32 v119, v119
	v_mul_f32_e32 v115, v128, v120
	v_mul_f32_e32 v115, v115, v118
	v_mul_f32_e32 v118, v129, v121
	v_fma_f32 v122, v122, v130, v74
	v_fma_f32 v123, v123, v130, v75
	v_mul_f32_e32 v118, v118, v119
	v_cvt_pk_bf16_f32 v115, v115, v118
	v_mul_f32_e32 v118, 0xbfb8aa3b, v122
	v_exp_f32_e32 v118, v118
	v_mul_f32_e32 v116, v122, v116
	v_fma_f32 v124, v124, v130, v76
	v_fma_f32 v125, v125, v130, v77
	v_mul_f32_e32 v117, v123, v117
	v_add_f32_e32 v118, 1.0, v118
	v_rcp_f32_e32 v118, v118
	v_mul_f32_e32 v119, 0xbfb8aa3b, v125
	v_exp_f32_e32 v119, v119
	v_lshl_add_u64 v[132:133], v[132:133], 0, v[164:165]
	v_mul_f32_e32 v116, v116, v118
	v_mul_f32_e32 v118, 0xbfb8aa3b, v123
	v_exp_f32_e32 v118, v118
	v_add_f32_e32 v119, 1.0, v119
	v_rcp_f32_e32 v119, v119
	v_add_f32_e32 v118, 1.0, v118
	v_rcp_f32_e32 v118, v118
	s_nop 0
	v_mul_f32_e32 v117, v117, v118
	v_mul_f32_e32 v118, 0xbfb8aa3b, v124
	v_exp_f32_e32 v118, v118
	v_cvt_pk_bf16_f32 v116, v116, v117
	v_mul_f32_e32 v117, v124, v134
	v_add_f32_e32 v118, 1.0, v118
	v_rcp_f32_e32 v118, v118
	s_nop 0
	v_mul_f32_e32 v117, v117, v118
	v_mul_f32_e32 v118, v125, v135
	v_mul_f32_e32 v118, v118, v119
	v_cvt_pk_bf16_f32 v117, v117, v118
	global_store_dwordx4 v[132:133], v[114:117], off
	ds_bpermute_b32 v114, v180, v183 offset:128
	s_nop 0
	v_or_b32_e32 v115, 32, v181
	v_mad_i64_i32 v[116:117], s[2:3], v115, s59, v[162:163]
	s_waitcnt lgkmcnt(0)
	v_fma_f32 v110, v110, v114, v78
	v_fma_f32 v111, v111, v114, v79
	v_fma_f32 v102, v102, v114, v70
	v_fma_f32 v103, v103, v114, v71
	v_fma_f32 v118, v100, v114, v68
	v_fma_f32 v119, v101, v114, v69
	v_fma_f32 v100, v98, v114, v66
	v_fma_f32 v101, v99, v114, v67
	v_mul_f32_e32 v99, 0xbfb8aa3b, v110
	v_mul_f32_e32 v98, v110, v102
	v_exp_f32_e32 v99, v99
	v_mul_f32_e32 v102, 0xbfb8aa3b, v111
	v_exp_f32_e32 v102, v102
	v_fma_f32 v112, v112, v114, v80
	v_fma_f32 v113, v113, v114, v81
	v_add_f32_e32 v99, 1.0, v99
	v_rcp_f32_e32 v99, v99
	v_add_f32_e32 v102, 1.0, v102
	v_rcp_f32_e32 v102, v102
	v_fma_f32 v104, v104, v114, v72
	v_fma_f32 v105, v105, v114, v73
	v_mul_f32_e32 v98, v98, v99
	v_mul_f32_e32 v99, v111, v103
	v_mul_f32_e32 v99, v99, v102
	v_mul_f32_e32 v102, 0xbfb8aa3b, v112
	v_exp_f32_e32 v102, v102
	v_mul_f32_e32 v103, 0xbfb8aa3b, v113
	v_exp_f32_e32 v103, v103
	v_cvt_pk_bf16_f32 v98, v98, v99
	v_add_f32_e32 v102, 1.0, v102
	v_rcp_f32_e32 v102, v102
	v_add_f32_e32 v103, 1.0, v103
	v_rcp_f32_e32 v103, v103
	v_mul_f32_e32 v99, v112, v104
	v_mul_f32_e32 v99, v99, v102
	v_mul_f32_e32 v102, v113, v105
	v_fma_f32 v106, v106, v114, v74
	v_fma_f32 v107, v107, v114, v75
	v_mul_f32_e32 v102, v102, v103
	v_cvt_pk_bf16_f32 v99, v99, v102
	v_mul_f32_e32 v102, 0xbfb8aa3b, v106
	v_exp_f32_e32 v102, v102
	v_mul_f32_e32 v100, v106, v100
	v_fma_f32 v108, v108, v114, v76
	v_fma_f32 v109, v109, v114, v77
	v_mul_f32_e32 v101, v107, v101
	v_add_f32_e32 v102, 1.0, v102
	v_rcp_f32_e32 v102, v102
	v_mul_f32_e32 v103, 0xbfb8aa3b, v109
	v_exp_f32_e32 v103, v103
	v_lshl_add_u64 v[116:117], v[116:117], 0, v[164:165]
	v_mul_f32_e32 v100, v100, v102
	v_mul_f32_e32 v102, 0xbfb8aa3b, v107
	v_exp_f32_e32 v102, v102
	v_add_f32_e32 v103, 1.0, v103
	v_rcp_f32_e32 v103, v103
	v_add_f32_e32 v102, 1.0, v102
	v_rcp_f32_e32 v102, v102
	s_nop 0
	v_mul_f32_e32 v101, v101, v102
	v_mul_f32_e32 v102, 0xbfb8aa3b, v108
	v_exp_f32_e32 v102, v102
	v_cvt_pk_bf16_f32 v100, v100, v101
	v_mul_f32_e32 v101, v108, v118
	v_add_f32_e32 v102, 1.0, v102
	v_rcp_f32_e32 v102, v102
	s_nop 0
	v_mul_f32_e32 v101, v101, v102
	v_mul_f32_e32 v102, v109, v119
	v_mul_f32_e32 v102, v102, v103
	v_cvt_pk_bf16_f32 v101, v101, v102
	global_store_dwordx4 v[116:117], v[98:101], off
	ds_bpermute_b32 v98, v180, v183 offset:192
	s_nop 0
	v_or_b32_e32 v99, 48, v181
	v_mad_i64_i32 v[100:101], s[2:3], v99, s59, v[162:163]
	s_waitcnt lgkmcnt(0)
; __device__ __forceinline__ unsigned cvt_pk_bf16(float lo, float hi) { unsigned r; asm volatile("v_cvt_pk_bf16_f32 %0, %1, %2" : "=v"(r) : "v"(lo), "v"(hi)); return r; }
; __device__ __forceinline__ float silu_mul(float a, float b) { return a * b * __builtin_amdgcn_rcpf(1.0f + __builtin_amdgcn_exp2f(-a * LOG2E)); }
; __device__ __forceinline__ float row_rstd(const float* ss, int row) { return 1.0f / sqrtf(ss[row] * (1.0f / DM) + 1e-6f); }
;     __device__ __forceinline__ void operator()(const f32x4 (&acc)[2][2][4][2], const Unit& u, int wr, int wc, int fr, int fq) const {
;     ...
;             for (int m = 0; m < 4; ++m) { const int row = row0 + ai * HALF + m * 16; const float rs = __shfl(ai ? rsl1 : rsl0, m * 16 + fr); bf16_t* rowp = O + (size_t)row * DFF + col0;
;                 const f32x4 a0 = acc[ai][0][m][0] * rs + ba0, a1 = acc[ai][0][m][1] * rs + ba1, b0 = acc[ai][1][m][0] * rs + bb0, b1 = acc[ai][1][m][1] * rs + bb1;
;                 u32x4 w; w.x = cvt_pk_bf16(silu_mul(a0[0], b0[0]), silu_mul(a0[1], b0[1])); w.y = cvt_pk_bf16(silu_mul(a0[2], b0[2]), silu_mul(a0[3], b0[3]));
;                 w.z = cvt_pk_bf16(silu_mul(a1[0], b1[0]), silu_mul(a1[1], b1[1])); w.w = cvt_pk_bf16(silu_mul(a1[2], b1[2]), silu_mul(a1[3], b1[3]));
;                 *(u32x4*)rowp = w; }
	v_fma_f32 v94, v94, v98, v78
	v_fma_f32 v95, v95, v98, v79
	v_fma_f32 v86, v86, v98, v70
	v_fma_f32 v87, v87, v98, v71
	v_fma_f32 v102, v84, v98, v68
	v_fma_f32 v103, v85, v98, v69
	v_fma_f32 v84, v82, v98, v66
	v_fma_f32 v85, v83, v98, v67
	v_mul_f32_e32 v83, 0xbfb8aa3b, v94
	v_mul_f32_e32 v82, v94, v86
	v_exp_f32_e32 v83, v83
	v_mul_f32_e32 v86, 0xbfb8aa3b, v95
	v_exp_f32_e32 v86, v86
	v_fma_f32 v96, v96, v98, v80
	v_fma_f32 v97, v97, v98, v81
	v_add_f32_e32 v83, 1.0, v83
	v_rcp_f32_e32 v83, v83
	v_add_f32_e32 v86, 1.0, v86
	v_rcp_f32_e32 v86, v86
	v_fma_f32 v88, v88, v98, v72
	v_fma_f32 v89, v89, v98, v73
	v_mul_f32_e32 v82, v82, v83
	v_mul_f32_e32 v83, v95, v87
	v_mul_f32_e32 v83, v83, v86
	v_mul_f32_e32 v86, 0xbfb8aa3b, v96
	v_exp_f32_e32 v86, v86
	v_mul_f32_e32 v87, 0xbfb8aa3b, v97
	v_exp_f32_e32 v87, v87
	v_cvt_pk_bf16_f32 v82, v82, v83
	v_add_f32_e32 v86, 1.0, v86
	v_rcp_f32_e32 v86, v86
	v_add_f32_e32 v87, 1.0, v87
	v_rcp_f32_e32 v87, v87
	v_mul_f32_e32 v83, v96, v88
	v_mul_f32_e32 v83, v83, v86
	v_mul_f32_e32 v86, v97, v89
	v_fma_f32 v90, v90, v98, v74
	v_fma_f32 v91, v91, v98, v75
	v_mul_f32_e32 v86, v86, v87
	v_cvt_pk_bf16_f32 v83, v83, v86
	v_mul_f32_e32 v86, 0xbfb8aa3b, v90
	v_exp_f32_e32 v86, v86
	v_mul_f32_e32 v84, v90, v84
	v_fma_f32 v92, v92, v98, v76
	v_fma_f32 v93, v93, v98, v77
	v_mul_f32_e32 v85, v91, v85
	v_add_f32_e32 v86, 1.0, v86
	v_rcp_f32_e32 v86, v86
	v_mul_f32_e32 v87, 0xbfb8aa3b, v93
	v_exp_f32_e32 v87, v87
	v_lshl_add_u64 v[100:101], v[100:101], 0, v[164:165]
	v_mul_f32_e32 v84, v84, v86
	v_mul_f32_e32 v86, 0xbfb8aa3b, v91
	v_exp_f32_e32 v86, v86
	v_add_f32_e32 v87, 1.0, v87
	v_rcp_f32_e32 v87, v87
	v_add_f32_e32 v86, 1.0, v86
	v_rcp_f32_e32 v86, v86
	s_nop 0
	v_mul_f32_e32 v85, v85, v86
	v_mul_f32_e32 v86, 0xbfb8aa3b, v92
	v_exp_f32_e32 v86, v86
	v_cvt_pk_bf16_f32 v84, v84, v85
	v_mul_f32_e32 v85, v92, v102
	v_add_f32_e32 v86, 1.0, v86
	v_rcp_f32_e32 v86, v86
	s_nop 0
	v_mul_f32_e32 v85, v85, v86
	v_mul_f32_e32 v86, v93, v103
	v_mul_f32_e32 v86, v86, v87
	v_cvt_pk_bf16_f32 v85, v85, v86
	global_store_dwordx4 v[100:101], v[82:85], off
	s_nop 1
	v_div_scale_f32 v82, s[2:3], v182, v182, 1.0
	v_rcp_f32_e32 v84, v82
	v_add_u32_e32 v83, 0x80, v181
	v_fma_f32 v85, -v82, v84, 1.0
	v_fmac_f32_e32 v84, v85, v84
	v_div_scale_f32 v85, vcc, 1.0, v182, 1.0
	v_mul_f32_e32 v86, v85, v84
	v_fma_f32 v87, -v82, v86, v85
	v_fmac_f32_e32 v86, v87, v84
	v_fma_f32 v82, -v82, v86, v85
	v_div_fmas_f32 v82, v82, v84, v86
	v_div_fixup_f32 v82, v82, v182, 1.0
	ds_bpermute_b32 v84, v180, v82
	v_mad_i64_i32 v[86:87], s[2:3], v83, s59, v[162:163]
	v_lshl_add_u64 v[86:87], v[86:87], 0, v[164:165]
	s_andn2_b64 vcc, exec, s[38:39]
	s_waitcnt lgkmcnt(0)
	v_fma_f32 v62, v62, v84, v78
	v_fma_f32 v63, v63, v84, v79
	v_fma_f32 v54, v54, v84, v70
	v_fma_f32 v55, v55, v84, v71
	v_fma_f32 v88, v52, v84, v68
	v_fma_f32 v89, v53, v84, v69
	v_fma_f32 v52, v50, v84, v66
	v_fma_f32 v53, v51, v84, v67
	v_mul_f32_e32 v51, 0xbfb8aa3b, v62
	v_mul_f32_e32 v50, v62, v54
	v_exp_f32_e32 v51, v51
	v_mul_f32_e32 v54, 0xbfb8aa3b, v63
	v_exp_f32_e32 v54, v54
	v_fma_f32 v64, v64, v84, v80
	v_fma_f32 v65, v65, v84, v81
	v_add_f32_e32 v51, 1.0, v51
	v_rcp_f32_e32 v51, v51
	v_add_f32_e32 v54, 1.0, v54
	v_rcp_f32_e32 v54, v54
	v_fma_f32 v56, v56, v84, v72
	v_fma_f32 v57, v57, v84, v73
	v_mul_f32_e32 v50, v50, v51
	v_mul_f32_e32 v51, v63, v55
	v_mul_f32_e32 v51, v51, v54
	v_mul_f32_e32 v54, 0xbfb8aa3b, v64
	v_exp_f32_e32 v54, v54
	v_mul_f32_e32 v55, 0xbfb8aa3b, v65
	v_exp_f32_e32 v55, v55
	v_cvt_pk_bf16_f32 v50, v50, v51
	v_add_f32_e32 v54, 1.0, v54
	v_rcp_f32_e32 v54, v54
	v_add_f32_e32 v55, 1.0, v55
	v_rcp_f32_e32 v55, v55
	v_mul_f32_e32 v51, v64, v56
	v_mul_f32_e32 v51, v51, v54
	v_mul_f32_e32 v54, v65, v57
	v_fma_f32 v58, v58, v84, v74
	v_fma_f32 v59, v59, v84, v75
	v_mul_f32_e32 v54, v54, v55
	v_cvt_pk_bf16_f32 v51, v51, v54
	v_mul_f32_e32 v54, 0xbfb8aa3b, v58
	v_exp_f32_e32 v54, v54
	v_mul_f32_e32 v52, v58, v52
	v_fma_f32 v60, v60, v84, v76
	v_fma_f32 v61, v61, v84, v77
	v_mul_f32_e32 v53, v59, v53
	v_add_f32_e32 v54, 1.0, v54
	v_rcp_f32_e32 v54, v54
	v_mul_f32_e32 v55, 0xbfb8aa3b, v61
	v_exp_f32_e32 v55, v55
	v_mul_f32_e32 v52, v52, v54
	v_mul_f32_e32 v54, 0xbfb8aa3b, v59
	v_exp_f32_e32 v54, v54
	v_add_f32_e32 v55, 1.0, v55
	v_rcp_f32_e32 v55, v55
	v_add_f32_e32 v54, 1.0, v54
	v_rcp_f32_e32 v54, v54
	s_nop 0
	v_mul_f32_e32 v53, v53, v54
	v_mul_f32_e32 v54, 0xbfb8aa3b, v60
	v_exp_f32_e32 v54, v54
	v_cvt_pk_bf16_f32 v52, v52, v53
	v_mul_f32_e32 v53, v60, v88
	v_add_f32_e32 v54, 1.0, v54
	v_rcp_f32_e32 v54, v54
	s_nop 0
	v_mul_f32_e32 v53, v53, v54
	v_mul_f32_e32 v54, v61, v89
	v_mul_f32_e32 v54, v54, v55
	v_cvt_pk_bf16_f32 v53, v53, v54
	global_store_dwordx4 v[86:87], v[50:53], off
	ds_bpermute_b32 v50, v180, v82 offset:64
	s_nop 0
	v_add_u32_e32 v51, 0x90, v181
	v_mad_i64_i32 v[52:53], s[2:3], v51, s59, v[162:163]
	s_waitcnt lgkmcnt(0)
; __device__ __forceinline__ unsigned cvt_pk_bf16(float lo, float hi) { unsigned r; asm volatile("v_cvt_pk_bf16_f32 %0, %1, %2" : "=v"(r) : "v"(lo), "v"(hi)); return r; }
; __device__ __forceinline__ float silu_mul(float a, float b) { return a * b * __builtin_amdgcn_rcpf(1.0f + __builtin_amdgcn_exp2f(-a * LOG2E)); }
; #define PG8_BAR __builtin_amdgcn_s_barrier()
;     __device__ __forceinline__ void operator()(const f32x4 (&acc)[2][2][4][2], const Unit& u, int wr, int wc, int fr, int fq) const {
;     ...
;             for (int m = 0; m < 4; ++m) { const int row = row0 + ai * HALF + m * 16; const float rs = __shfl(ai ? rsl1 : rsl0, m * 16 + fr); bf16_t* rowp = O + (size_t)row * DFF + col0;
;                 const f32x4 a0 = acc[ai][0][m][0] * rs + ba0, a1 = acc[ai][0][m][1] * rs + ba1, b0 = acc[ai][1][m][0] * rs + bb0, b1 = acc[ai][1][m][1] * rs + bb1;
;                 u32x4 w; w.x = cvt_pk_bf16(silu_mul(a0[0], b0[0]), silu_mul(a0[1], b0[1])); w.y = cvt_pk_bf16(silu_mul(a0[2], b0[2]), silu_mul(a0[3], b0[3]));
;                 w.z = cvt_pk_bf16(silu_mul(a1[0], b1[0]), silu_mul(a1[1], b1[1])); w.w = cvt_pk_bf16(silu_mul(a1[2], b1[2]), silu_mul(a1[3], b1[3]));
;                 *(u32x4*)rowp = w; }
; template <class Epi, class Sched, bool ALIGN_EPI = false, bool SP2 = false>
; __device__ __forceinline__ void gemm_phase(LAS unsigned char* lds, const Gemm g, const Sched& S, const Epi& E) {
;     ...
;         if constexpr (!Epi::AFTER_DRAIN) { E(acc, cur, wr, wc, fr, fq); S.done(cur); }
;         if (!has_next) break;
; #pragma unroll
;         for (int a = 0; a < 2; ++a)
; #pragma unroll
;             for (int b = 0; b < 2; ++b)
; #pragma unroll
;                 for (int m = 0; m < 4; ++m)
; #pragma unroll
;                     for (int n = 0; n < 2; ++n) acc[a][b][m][n] = (f32x4){0.f, 0.f, 0.f, 0.f};
;         cur = nxt; cA = nA; cB = nB; ++ui;
;         if constexpr (ALIGN_EPI) { if (wr == 1) PG8_BAR; }
	v_fma_f32 v46, v46, v50, v78
	v_fma_f32 v47, v47, v50, v79
	v_fma_f32 v38, v38, v50, v70
	v_fma_f32 v39, v39, v50, v71
	v_fma_f32 v54, v36, v50, v68
	v_fma_f32 v55, v37, v50, v69
	v_fma_f32 v36, v34, v50, v66
	v_fma_f32 v37, v35, v50, v67
	v_mul_f32_e32 v35, 0xbfb8aa3b, v46
	v_mul_f32_e32 v34, v46, v38
	v_exp_f32_e32 v35, v35
	v_mul_f32_e32 v38, 0xbfb8aa3b, v47
	v_exp_f32_e32 v38, v38
	v_fma_f32 v48, v48, v50, v80
	v_fma_f32 v49, v49, v50, v81
	v_add_f32_e32 v35, 1.0, v35
	v_rcp_f32_e32 v35, v35
	v_add_f32_e32 v38, 1.0, v38
	v_rcp_f32_e32 v38, v38
	v_fma_f32 v40, v40, v50, v72
	v_fma_f32 v41, v41, v50, v73
	v_mul_f32_e32 v34, v34, v35
	v_mul_f32_e32 v35, v47, v39
	v_mul_f32_e32 v35, v35, v38
	v_mul_f32_e32 v38, 0xbfb8aa3b, v48
	v_exp_f32_e32 v38, v38
	v_mul_f32_e32 v39, 0xbfb8aa3b, v49
	v_exp_f32_e32 v39, v39
	v_cvt_pk_bf16_f32 v34, v34, v35
	v_add_f32_e32 v38, 1.0, v38
	v_rcp_f32_e32 v38, v38
	v_add_f32_e32 v39, 1.0, v39
	v_rcp_f32_e32 v39, v39
	v_mul_f32_e32 v35, v48, v40
	v_mul_f32_e32 v35, v35, v38
	v_mul_f32_e32 v38, v49, v41
	v_fma_f32 v42, v42, v50, v74
	v_fma_f32 v43, v43, v50, v75
	v_mul_f32_e32 v38, v38, v39
	v_cvt_pk_bf16_f32 v35, v35, v38
	v_mul_f32_e32 v38, 0xbfb8aa3b, v42
	v_exp_f32_e32 v38, v38
	v_mul_f32_e32 v36, v42, v36
	v_fma_f32 v44, v44, v50, v76
	v_fma_f32 v45, v45, v50, v77
	v_mul_f32_e32 v37, v43, v37
	v_add_f32_e32 v38, 1.0, v38
	v_rcp_f32_e32 v38, v38
	v_mul_f32_e32 v39, 0xbfb8aa3b, v45
	v_exp_f32_e32 v39, v39
	v_lshl_add_u64 v[52:53], v[52:53], 0, v[164:165]
	v_mul_f32_e32 v36, v36, v38
	v_mul_f32_e32 v38, 0xbfb8aa3b, v43
	v_exp_f32_e32 v38, v38
	v_add_f32_e32 v39, 1.0, v39
	v_rcp_f32_e32 v39, v39
	v_add_f32_e32 v38, 1.0, v38
	v_rcp_f32_e32 v38, v38
	s_nop 0
	v_mul_f32_e32 v37, v37, v38
	v_mul_f32_e32 v38, 0xbfb8aa3b, v44
	v_exp_f32_e32 v38, v38
	v_cvt_pk_bf16_f32 v36, v36, v37
	v_mul_f32_e32 v37, v44, v54
	v_add_f32_e32 v38, 1.0, v38
	v_rcp_f32_e32 v38, v38
	s_nop 0
	v_mul_f32_e32 v37, v37, v38
	v_mul_f32_e32 v38, v45, v55
	v_mul_f32_e32 v38, v38, v39
	v_cvt_pk_bf16_f32 v37, v37, v38
	global_store_dwordx4 v[52:53], v[34:37], off
	ds_bpermute_b32 v34, v180, v82 offset:128
	s_nop 0
	v_add_u32_e32 v35, 0xa0, v181
	v_mad_i64_i32 v[36:37], s[2:3], v35, s59, v[162:163]
	s_waitcnt lgkmcnt(0)
	v_fma_f32 v30, v30, v34, v78
	v_fma_f32 v31, v31, v34, v79
	v_fma_f32 v22, v22, v34, v70
	v_fma_f32 v23, v23, v34, v71
	v_fma_f32 v38, v20, v34, v68
	v_fma_f32 v39, v21, v34, v69
	v_fma_f32 v20, v18, v34, v66
	v_fma_f32 v21, v19, v34, v67
	v_mul_f32_e32 v19, 0xbfb8aa3b, v30
	v_mul_f32_e32 v18, v30, v22
	v_exp_f32_e32 v19, v19
	v_mul_f32_e32 v22, 0xbfb8aa3b, v31
	v_exp_f32_e32 v22, v22
	v_fma_f32 v32, v32, v34, v80
	v_fma_f32 v33, v33, v34, v81
	v_add_f32_e32 v19, 1.0, v19
	v_rcp_f32_e32 v19, v19
	v_add_f32_e32 v22, 1.0, v22
	v_rcp_f32_e32 v22, v22
	v_fma_f32 v24, v24, v34, v72
	v_fma_f32 v25, v25, v34, v73
	v_mul_f32_e32 v18, v18, v19
	v_mul_f32_e32 v19, v31, v23
	v_mul_f32_e32 v19, v19, v22
	v_mul_f32_e32 v22, 0xbfb8aa3b, v32
	v_exp_f32_e32 v22, v22
	v_mul_f32_e32 v23, 0xbfb8aa3b, v33
	v_exp_f32_e32 v23, v23
	v_cvt_pk_bf16_f32 v18, v18, v19
	v_add_f32_e32 v22, 1.0, v22
	v_rcp_f32_e32 v22, v22
	v_add_f32_e32 v23, 1.0, v23
	v_rcp_f32_e32 v23, v23
	v_mul_f32_e32 v19, v32, v24
	v_mul_f32_e32 v19, v19, v22
	v_mul_f32_e32 v22, v33, v25
	v_fma_f32 v26, v26, v34, v74
	v_fma_f32 v27, v27, v34, v75
	v_mul_f32_e32 v22, v22, v23
	v_cvt_pk_bf16_f32 v19, v19, v22
	v_mul_f32_e32 v22, 0xbfb8aa3b, v26
	v_exp_f32_e32 v22, v22
	v_mul_f32_e32 v20, v26, v20
	v_fma_f32 v28, v28, v34, v76
	v_fma_f32 v29, v29, v34, v77
	v_mul_f32_e32 v21, v27, v21
	v_add_f32_e32 v22, 1.0, v22
	v_rcp_f32_e32 v22, v22
	v_mul_f32_e32 v23, 0xbfb8aa3b, v29
	v_exp_f32_e32 v23, v23
	v_lshl_add_u64 v[36:37], v[36:37], 0, v[164:165]
	v_mul_f32_e32 v20, v20, v22
	v_mul_f32_e32 v22, 0xbfb8aa3b, v27
	v_exp_f32_e32 v22, v22
	v_add_f32_e32 v23, 1.0, v23
	v_rcp_f32_e32 v23, v23
	v_add_f32_e32 v22, 1.0, v22
	v_rcp_f32_e32 v22, v22
	s_nop 0
	v_mul_f32_e32 v21, v21, v22
	v_mul_f32_e32 v22, 0xbfb8aa3b, v28
	v_exp_f32_e32 v22, v22
	v_cvt_pk_bf16_f32 v20, v20, v21
	v_mul_f32_e32 v21, v28, v38
	v_add_f32_e32 v22, 1.0, v22
	v_rcp_f32_e32 v22, v22
	s_nop 0
	v_mul_f32_e32 v21, v21, v22
	v_mul_f32_e32 v22, v29, v39
	v_mul_f32_e32 v22, v22, v23
	v_cvt_pk_bf16_f32 v21, v21, v22
	global_store_dwordx4 v[36:37], v[18:21], off
	ds_bpermute_b32 v18, v180, v82 offset:192
	s_nop 0
	v_add_u32_e32 v19, 0xb0, v181
	v_mad_i64_i32 v[20:21], s[2:3], v19, s59, v[162:163]
	s_waitcnt lgkmcnt(0)
	v_fma_f32 v14, v14, v18, v78
	v_fma_f32 v15, v15, v18, v79
	v_fma_f32 v6, v6, v18, v70
	v_fma_f32 v7, v7, v18, v71
	v_fma_f32 v22, v4, v18, v68
	v_fma_f32 v23, v5, v18, v69
	v_fma_f32 v4, v2, v18, v66
	v_fma_f32 v5, v3, v18, v67
	v_mul_f32_e32 v3, 0xbfb8aa3b, v14
	v_mul_f32_e32 v2, v14, v6
	v_exp_f32_e32 v3, v3
	v_mul_f32_e32 v6, 0xbfb8aa3b, v15
	v_exp_f32_e32 v6, v6
	v_fma_f32 v16, v16, v18, v80
	v_fma_f32 v17, v17, v18, v81
	v_add_f32_e32 v3, 1.0, v3
	v_rcp_f32_e32 v3, v3
	v_add_f32_e32 v6, 1.0, v6
	v_rcp_f32_e32 v6, v6
	v_fma_f32 v8, v8, v18, v72
	v_fma_f32 v9, v9, v18, v73
	v_mul_f32_e32 v2, v2, v3
	v_mul_f32_e32 v3, v15, v7
	v_mul_f32_e32 v3, v3, v6
	v_mul_f32_e32 v6, 0xbfb8aa3b, v16
	v_exp_f32_e32 v6, v6
	v_mul_f32_e32 v7, 0xbfb8aa3b, v17
	v_exp_f32_e32 v7, v7
	v_cvt_pk_bf16_f32 v2, v2, v3
	v_add_f32_e32 v6, 1.0, v6
	v_rcp_f32_e32 v6, v6
	v_add_f32_e32 v7, 1.0, v7
	v_rcp_f32_e32 v7, v7
	v_mul_f32_e32 v3, v16, v8
	v_mul_f32_e32 v3, v3, v6
	v_mul_f32_e32 v6, v17, v9
	v_fma_f32 v10, v10, v18, v74
	v_fma_f32 v11, v11, v18, v75
	v_mul_f32_e32 v6, v6, v7
	v_cvt_pk_bf16_f32 v3, v3, v6
	v_mul_f32_e32 v6, 0xbfb8aa3b, v10
	v_exp_f32_e32 v6, v6
	v_mul_f32_e32 v4, v10, v4
	v_fma_f32 v12, v12, v18, v76
	v_fma_f32 v13, v13, v18, v77
	v_mul_f32_e32 v5, v11, v5
	v_add_f32_e32 v6, 1.0, v6
	v_rcp_f32_e32 v6, v6
	v_mul_f32_e32 v7, 0xbfb8aa3b, v13
	v_exp_f32_e32 v7, v7
	v_lshl_add_u64 v[20:21], v[20:21], 0, v[164:165]
	v_mul_f32_e32 v4, v4, v6
	v_mul_f32_e32 v6, 0xbfb8aa3b, v11
	v_exp_f32_e32 v6, v6
	v_add_f32_e32 v7, 1.0, v7
	v_rcp_f32_e32 v7, v7
	s_mov_b64 s[2:3], -1
	v_add_f32_e32 v6, 1.0, v6
	v_rcp_f32_e32 v6, v6
	s_nop 0
	v_mul_f32_e32 v5, v5, v6
	v_mul_f32_e32 v6, 0xbfb8aa3b, v12
	v_exp_f32_e32 v6, v6
	v_cvt_pk_bf16_f32 v4, v4, v5
	v_mul_f32_e32 v5, v12, v22
	v_add_f32_e32 v6, 1.0, v6
	v_rcp_f32_e32 v6, v6
	s_nop 0
	v_mul_f32_e32 v5, v5, v6
	v_mul_f32_e32 v6, v13, v23
	v_mul_f32_e32 v6, v6, v7
	v_cvt_pk_bf16_f32 v5, v5, v6
	global_store_dwordx4 v[20:21], v[2:5], off
	s_cbranch_vccnz .LBB0_184
	s_andn2_b64 vcc, exec, s[4:5]
	s_cbranch_vccnz .LBB0_183
	s_barrier
	s_branch .LBB0_183

; __device__ __forceinline__ unsigned cvt_pk_bf16(float lo, float hi) { unsigned r; asm volatile("v_cvt_pk_bf16_f32 %0, %1, %2" : "=v"(r) : "v"(lo), "v"(hi)); return r; }
; __device__ __forceinline__ float silu_mul(float a, float b) { return a * b * __builtin_amdgcn_rcpf(1.0f + __builtin_amdgcn_exp2f(-a * LOG2E)); }
; __device__ __forceinline__ float row_rstd(const float* ss, int row) { return 1.0f / sqrtf(ss[row] * (1.0f / DM) + 1e-6f); }
;     __device__ __forceinline__ void operator()(const f32x4 (&acc)[2][2][4][2], const Unit& u, int wr, int wc, int fr, int fq) const {
;         const int row0 = u.pm * BM + wr * 64 + fr, col0 = u.pn * HALF + wc * 32 + 8 * fq;
;         const int s = (u.pm < ML / BM) ? (u.pm >> 5) : 4;
;         const float* bp = bias + (size_t)s * BIAS_N + u.pn * BM + wc * 32 + 8 * fq;
;         const f32x4 ba0 = *(const f32x4*)bp, ba1 = *(const f32x4*)(bp + 4), bb0 = *(const f32x4*)(bp + HALF), bb1 = *(const f32x4*)(bp + HALF + 4);
;         const int lane = fq * 16 + fr;
;         const float rsl0 = row_rstd(ss, u.pm * BM + wr * 64 + lane), rsl1 = row_rstd(ss, u.pm * BM + HALF + wr * 64 + lane);
; #pragma unroll
;         for (int ai = 0; ai < 2; ++ai)
; #pragma unroll
;             for (int m = 0; m < 4; ++m) { const int row = row0 + ai * HALF + m * 16; const float rs = __shfl(ai ? rsl1 : rsl0, m * 16 + fr); bf16_t* rowp = O + (size_t)row * DFF + col0;
;                 const f32x4 a0 = acc[ai][0][m][0] * rs + ba0, a1 = acc[ai][0][m][1] * rs + ba1, b0 = acc[ai][1][m][0] * rs + bb0, b1 = acc[ai][1][m][1] * rs + bb1;
;                 u32x4 w; w.x = cvt_pk_bf16(silu_mul(a0[0], b0[0]), silu_mul(a0[1], b0[1])); w.y = cvt_pk_bf16(silu_mul(a0[2], b0[2]), silu_mul(a0[3], b0[3]));
;                 w.z = cvt_pk_bf16(silu_mul(a1[0], b1[0]), silu_mul(a1[1], b1[1])); w.w = cvt_pk_bf16(silu_mul(a1[2], b1[2]), silu_mul(a1[3], b1[3]));
;                 *(u32x4*)rowp = w; }
.LBB0_1470:
	s_lshl_b32 s2, s2, 8
	s_add_i32 s13, s2, s42
	s_lshl_b64 s[2:3], s[16:17], 2
	s_add_u32 s15, s43, s2
	s_addc_u32 s16, s44, s3
	s_lshl_b32 s2, s0, 8
	s_ashr_i32 s3, s2, 31
	s_lshl_b64 s[2:3], s[2:3], 2
	v_lshl_or_b32 v164, s0, 7, v173
	s_add_u32 s0, s15, s2
	s_addc_u32 s3, s16, s3
	v_or_b32_e32 v162, s13, v171
	s_add_u32 s2, s0, s50
	v_ashrrev_i32_e32 v163, 31, v162
	s_addc_u32 s3, s3, 0
	v_lshl_add_u64 v[162:163], v[162:163], 2, s[64:65]
	v_mov_b32_e32 v74, v234
	v_mov_b32_e32 v75, v235
	v_mov_b32_e32 v76, v236
	v_mov_b32_e32 v77, v237
	v_mov_b32_e32 v78, v238
	v_mov_b32_e32 v79, v239
	v_mov_b32_e32 v80, v240
	v_mov_b32_e32 v81, v241
	v_mov_b32_e32 v66, v242
	v_mov_b32_e32 v67, v243
	v_mov_b32_e32 v68, v244
	v_mov_b32_e32 v69, v245
	v_mov_b32_e32 v70, v246
	v_mov_b32_e32 v71, v247
	v_mov_b32_e32 v72, v248
	v_mov_b32_e32 v73, v249
	v_or_b32_e32 v181, s13, v169
	v_mov_b32_e32 v162, v250
	s_waitcnt vmcnt(0)
	v_fmamk_f32 v162, v162, 0x3a000000, v178
	v_cmp_gt_f32_e32 vcc, s51, v162
	v_mul_f32_e32 v163, 0x4f800000, v162
	s_nop 0
	v_cndmask_b32_e32 v162, v162, v163, vcc
	v_sqrt_f32_e32 v163, v162
	s_nop 0
	v_add_u32_e32 v165, -1, v163
	v_fma_f32 v166, -v165, v163, v162
	v_cmp_ge_f32_e64 s[2:3], 0, v166
	v_add_u32_e32 v166, 1, v163
	s_nop 0
	v_cndmask_b32_e64 v165, v163, v165, s[2:3]
	v_fma_f32 v163, -v166, v163, v162
	v_cmp_lt_f32_e64 s[2:3], 0, v163
	s_nop 1
	v_cndmask_b32_e64 v163, v165, v166, s[2:3]
	v_mul_f32_e32 v165, 0x37800000, v163
	v_cndmask_b32_e32 v163, v163, v165, vcc
	v_cmp_class_f32_e32 vcc, v162, v179
	s_nop 1
	v_cndmask_b32_e32 v166, v163, v162, vcc
	v_add_u32_e32 v162, s13, v172
	v_ashrrev_i32_e32 v163, 31, v162
	v_lshl_add_u64 v[162:163], v[162:163], 2, s[64:65]
	v_mov_b32_e32 v162, v251
	v_fmamk_f32 v162, v162, 0x3a000000, v178
	v_cmp_gt_f32_e32 vcc, s51, v162
	v_mul_f32_e32 v163, 0x4f800000, v162
	s_nop 0
	v_cndmask_b32_e32 v162, v162, v163, vcc
	v_sqrt_f32_e32 v163, v162
	s_nop 0
	v_add_u32_e32 v165, -1, v163
	v_fma_f32 v167, -v165, v163, v162
	v_cmp_ge_f32_e64 s[2:3], 0, v167
	v_add_u32_e32 v167, 1, v163
	s_nop 0
	v_cndmask_b32_e64 v165, v163, v165, s[2:3]
	v_fma_f32 v163, -v167, v163, v162
	v_cmp_lt_f32_e64 s[2:3], 0, v163
	s_nop 1
	v_cndmask_b32_e64 v163, v165, v167, s[2:3]
	v_mul_f32_e32 v165, 0x37800000, v163
	v_cndmask_b32_e32 v163, v163, v165, vcc
	v_cmp_class_f32_e32 vcc, v162, v179
	v_ashrrev_i32_e32 v165, 31, v164
	v_lshlrev_b64 v[164:165], 1, v[164:165]
	v_cndmask_b32_e32 v182, v163, v162, vcc
	v_div_scale_f32 v162, s[2:3], v166, v166, 1.0
	v_rcp_f32_e32 v163, v162
	s_nop 0
	v_fma_f32 v167, -v162, v163, 1.0
	v_fmac_f32_e32 v163, v167, v163
	v_div_scale_f32 v167, vcc, 1.0, v166, 1.0
	v_mul_f32_e32 v168, v167, v163
	v_fma_f32 v183, -v162, v168, v167
	v_fmac_f32_e32 v168, v183, v163
	v_fma_f32 v162, -v162, v168, v167
	v_div_fmas_f32 v162, v162, v163, v168
	v_div_fixup_f32 v183, v162, v166, 1.0
	ds_bpermute_b32 v168, v180, v183
	v_mov_b64_e32 v[162:163], s[96:97]
	v_mad_i64_i32 v[166:167], s[2:3], v181, s49, v[162:163]
	v_lshl_add_u64 v[166:167], v[166:167], 0, v[164:165]
	s_waitcnt lgkmcnt(0)
	v_fma_f32 v142, v142, v168, v78
	v_fma_f32 v143, v143, v168, v79
	v_fma_f32 v134, v134, v168, v70
	v_fma_f32 v135, v135, v168, v71
	v_fma_f32 v184, v132, v168, v68
	v_fma_f32 v185, v133, v168, v69
	v_fma_f32 v132, v130, v168, v66
	v_fma_f32 v133, v131, v168, v67
	v_mul_f32_e32 v131, 0xbfb8aa3b, v142
	v_mul_f32_e32 v130, v142, v134
	v_exp_f32_e32 v131, v131
	v_mul_f32_e32 v134, 0xbfb8aa3b, v143
	v_exp_f32_e32 v134, v134
	v_fma_f32 v144, v144, v168, v80
	v_fma_f32 v145, v145, v168, v81
	v_add_f32_e32 v131, 1.0, v131
	v_rcp_f32_e32 v131, v131
	v_add_f32_e32 v134, 1.0, v134
	v_rcp_f32_e32 v134, v134
	v_fma_f32 v136, v136, v168, v72
	v_fma_f32 v137, v137, v168, v73
	v_mul_f32_e32 v130, v130, v131
	v_mul_f32_e32 v131, v143, v135
	v_mul_f32_e32 v131, v131, v134
	v_mul_f32_e32 v134, 0xbfb8aa3b, v144
	v_exp_f32_e32 v134, v134
	v_mul_f32_e32 v135, 0xbfb8aa3b, v145
	v_exp_f32_e32 v135, v135
	v_cvt_pk_bf16_f32 v130, v130, v131
	v_add_f32_e32 v134, 1.0, v134
	v_rcp_f32_e32 v134, v134
	v_add_f32_e32 v135, 1.0, v135
	v_rcp_f32_e32 v135, v135
	v_mul_f32_e32 v131, v144, v136
	v_mul_f32_e32 v131, v131, v134
	v_mul_f32_e32 v134, v145, v137
	v_fma_f32 v138, v138, v168, v74
	v_fma_f32 v139, v139, v168, v75
	v_mul_f32_e32 v134, v134, v135
	v_cvt_pk_bf16_f32 v131, v131, v134
	v_mul_f32_e32 v134, 0xbfb8aa3b, v138
	v_exp_f32_e32 v134, v134
	v_mul_f32_e32 v132, v138, v132
	v_fma_f32 v140, v140, v168, v76
	v_fma_f32 v141, v141, v168, v77
	v_mul_f32_e32 v133, v139, v133
	v_add_f32_e32 v134, 1.0, v134
	v_rcp_f32_e32 v134, v134
	v_mul_f32_e32 v135, 0xbfb8aa3b, v141
	v_exp_f32_e32 v135, v135
	v_mul_f32_e32 v132, v132, v134
	v_mul_f32_e32 v134, 0xbfb8aa3b, v139
	v_exp_f32_e32 v134, v134
	v_add_f32_e32 v135, 1.0, v135
	v_rcp_f32_e32 v135, v135
	v_add_f32_e32 v134, 1.0, v134
	v_rcp_f32_e32 v134, v134
	s_nop 0
	v_mul_f32_e32 v133, v133, v134
	v_mul_f32_e32 v134, 0xbfb8aa3b, v140
	v_exp_f32_e32 v134, v134
	v_cvt_pk_bf16_f32 v132, v132, v133
	v_mul_f32_e32 v133, v140, v184
	v_add_f32_e32 v134, 1.0, v134
	v_rcp_f32_e32 v134, v134
	s_nop 0
	v_mul_f32_e32 v133, v133, v134
	v_mul_f32_e32 v134, v141, v185
	v_mul_f32_e32 v134, v134, v135
	v_cvt_pk_bf16_f32 v133, v133, v134
	global_store_dwordx4 v[166:167], v[130:133], off
	ds_bpermute_b32 v130, v180, v183 offset:64
	s_nop 0
	v_or_b32_e32 v131, 16, v181
	v_mad_i64_i32 v[132:133], s[2:3], v131, s49, v[162:163]
	s_waitcnt lgkmcnt(0)
; __device__ __forceinline__ unsigned cvt_pk_bf16(float lo, float hi) { unsigned r; asm volatile("v_cvt_pk_bf16_f32 %0, %1, %2" : "=v"(r) : "v"(lo), "v"(hi)); return r; }
; __device__ __forceinline__ float silu_mul(float a, float b) { return a * b * __builtin_amdgcn_rcpf(1.0f + __builtin_amdgcn_exp2f(-a * LOG2E)); }
;     __device__ __forceinline__ void operator()(const f32x4 (&acc)[2][2][4][2], const Unit& u, int wr, int wc, int fr, int fq) const {
;     ...
;             for (int m = 0; m < 4; ++m) { const int row = row0 + ai * HALF + m * 16; const float rs = __shfl(ai ? rsl1 : rsl0, m * 16 + fr); bf16_t* rowp = O + (size_t)row * DFF + col0;
;                 const f32x4 a0 = acc[ai][0][m][0] * rs + ba0, a1 = acc[ai][0][m][1] * rs + ba1, b0 = acc[ai][1][m][0] * rs + bb0, b1 = acc[ai][1][m][1] * rs + bb1;
;                 u32x4 w; w.x = cvt_pk_bf16(silu_mul(a0[0], b0[0]), silu_mul(a0[1], b0[1])); w.y = cvt_pk_bf16(silu_mul(a0[2], b0[2]), silu_mul(a0[3], b0[3]));
;                 w.z = cvt_pk_bf16(silu_mul(a1[0], b1[0]), silu_mul(a1[1], b1[1])); w.w = cvt_pk_bf16(silu_mul(a1[2], b1[2]), silu_mul(a1[3], b1[3]));
;                 *(u32x4*)rowp = w; }
	v_fma_f32 v126, v126, v130, v78
	v_fma_f32 v127, v127, v130, v79
	v_fma_f32 v118, v118, v130, v70
	v_fma_f32 v119, v119, v130, v71
	v_fma_f32 v134, v116, v130, v68
	v_fma_f32 v135, v117, v130, v69
	v_fma_f32 v116, v114, v130, v66
	v_fma_f32 v117, v115, v130, v67
	v_mul_f32_e32 v115, 0xbfb8aa3b, v126
	v_mul_f32_e32 v114, v126, v118
	v_exp_f32_e32 v115, v115
	v_mul_f32_e32 v118, 0xbfb8aa3b, v127
	v_exp_f32_e32 v118, v118
	v_fma_f32 v128, v128, v130, v80
	v_fma_f32 v129, v129, v130, v81
	v_add_f32_e32 v115, 1.0, v115
	v_rcp_f32_e32 v115, v115
	v_add_f32_e32 v118, 1.0, v118
	v_rcp_f32_e32 v118, v118
	v_fma_f32 v120, v120, v130, v72
	v_fma_f32 v121, v121, v130, v73
	v_mul_f32_e32 v114, v114, v115
	v_mul_f32_e32 v115, v127, v119
	v_mul_f32_e32 v115, v115, v118
	v_mul_f32_e32 v118, 0xbfb8aa3b, v128
	v_exp_f32_e32 v118, v118
	v_mul_f32_e32 v119, 0xbfb8aa3b, v129
	v_exp_f32_e32 v119, v119
	v_cvt_pk_bf16_f32 v114, v114, v115
	v_add_f32_e32 v118, 1.0, v118
	v_rcp_f32_e32 v118, v118
	v_add_f32_e32 v119, 1.0, v119
	v_rcp_f32_e32 v119, v119
	v_mul_f32_e32 v115, v128, v120
	v_mul_f32_e32 v115, v115, v118
	v_mul_f32_e32 v118, v129, v121
	v_fma_f32 v122, v122, v130, v74
	v_fma_f32 v123, v123, v130, v75
	v_mul_f32_e32 v118, v118, v119
	v_cvt_pk_bf16_f32 v115, v115, v118
	v_mul_f32_e32 v118, 0xbfb8aa3b, v122
	v_exp_f32_e32 v118, v118
	v_mul_f32_e32 v116, v122, v116
	v_fma_f32 v124, v124, v130, v76
	v_fma_f32 v125, v125, v130, v77
	v_mul_f32_e32 v117, v123, v117
	v_add_f32_e32 v118, 1.0, v118
	v_rcp_f32_e32 v118, v118
	v_mul_f32_e32 v119, 0xbfb8aa3b, v125
	v_exp_f32_e32 v119, v119
	v_lshl_add_u64 v[132:133], v[132:133], 0, v[164:165]
	v_mul_f32_e32 v116, v116, v118
	v_mul_f32_e32 v118, 0xbfb8aa3b, v123
	v_exp_f32_e32 v118, v118
	v_add_f32_e32 v119, 1.0, v119
	v_rcp_f32_e32 v119, v119
	v_add_f32_e32 v118, 1.0, v118
	v_rcp_f32_e32 v118, v118
	s_nop 0
	v_mul_f32_e32 v117, v117, v118
	v_mul_f32_e32 v118, 0xbfb8aa3b, v124
	v_exp_f32_e32 v118, v118
	v_cvt_pk_bf16_f32 v116, v116, v117
	v_mul_f32_e32 v117, v124, v134
	v_add_f32_e32 v118, 1.0, v118
	v_rcp_f32_e32 v118, v118
	s_nop 0
	v_mul_f32_e32 v117, v117, v118
	v_mul_f32_e32 v118, v125, v135
	v_mul_f32_e32 v118, v118, v119
	v_cvt_pk_bf16_f32 v117, v117, v118
	global_store_dwordx4 v[132:133], v[114:117], off
	ds_bpermute_b32 v114, v180, v183 offset:128
	s_nop 0
	v_or_b32_e32 v115, 32, v181
	v_mad_i64_i32 v[116:117], s[2:3], v115, s49, v[162:163]
	s_waitcnt lgkmcnt(0)
	v_fma_f32 v110, v110, v114, v78
	v_fma_f32 v111, v111, v114, v79
	v_fma_f32 v102, v102, v114, v70
	v_fma_f32 v103, v103, v114, v71
	v_fma_f32 v118, v100, v114, v68
	v_fma_f32 v119, v101, v114, v69
	v_fma_f32 v100, v98, v114, v66
	v_fma_f32 v101, v99, v114, v67
	v_mul_f32_e32 v99, 0xbfb8aa3b, v110
	v_mul_f32_e32 v98, v110, v102
	v_exp_f32_e32 v99, v99
	v_mul_f32_e32 v102, 0xbfb8aa3b, v111
	v_exp_f32_e32 v102, v102
	v_fma_f32 v112, v112, v114, v80
	v_fma_f32 v113, v113, v114, v81
	v_add_f32_e32 v99, 1.0, v99
	v_rcp_f32_e32 v99, v99
	v_add_f32_e32 v102, 1.0, v102
	v_rcp_f32_e32 v102, v102
	v_fma_f32 v104, v104, v114, v72
	v_fma_f32 v105, v105, v114, v73
	v_mul_f32_e32 v98, v98, v99
	v_mul_f32_e32 v99, v111, v103
	v_mul_f32_e32 v99, v99, v102
	v_mul_f32_e32 v102, 0xbfb8aa3b, v112
	v_exp_f32_e32 v102, v102
	v_mul_f32_e32 v103, 0xbfb8aa3b, v113
	v_exp_f32_e32 v103, v103
	v_cvt_pk_bf16_f32 v98, v98, v99
	v_add_f32_e32 v102, 1.0, v102
	v_rcp_f32_e32 v102, v102
	v_add_f32_e32 v103, 1.0, v103
	v_rcp_f32_e32 v103, v103
	v_mul_f32_e32 v99, v112, v104
	v_mul_f32_e32 v99, v99, v102
	v_mul_f32_e32 v102, v113, v105
	v_fma_f32 v106, v106, v114, v74
	v_fma_f32 v107, v107, v114, v75
	v_mul_f32_e32 v102, v102, v103
	v_cvt_pk_bf16_f32 v99, v99, v102
	v_mul_f32_e32 v102, 0xbfb8aa3b, v106
	v_exp_f32_e32 v102, v102
	v_mul_f32_e32 v100, v106, v100
	v_fma_f32 v108, v108, v114, v76
	v_fma_f32 v109, v109, v114, v77
	v_mul_f32_e32 v101, v107, v101
	v_add_f32_e32 v102, 1.0, v102
	v_rcp_f32_e32 v102, v102
	v_mul_f32_e32 v103, 0xbfb8aa3b, v109
	v_exp_f32_e32 v103, v103
	v_lshl_add_u64 v[116:117], v[116:117], 0, v[164:165]
	v_mul_f32_e32 v100, v100, v102
	v_mul_f32_e32 v102, 0xbfb8aa3b, v107
	v_exp_f32_e32 v102, v102
	v_add_f32_e32 v103, 1.0, v103
	v_rcp_f32_e32 v103, v103
	v_add_f32_e32 v102, 1.0, v102
	v_rcp_f32_e32 v102, v102
	s_nop 0
	v_mul_f32_e32 v101, v101, v102
	v_mul_f32_e32 v102, 0xbfb8aa3b, v108
	v_exp_f32_e32 v102, v102
	v_cvt_pk_bf16_f32 v100, v100, v101
	v_mul_f32_e32 v101, v108, v118
	v_add_f32_e32 v102, 1.0, v102
	v_rcp_f32_e32 v102, v102
	s_nop 0
	v_mul_f32_e32 v101, v101, v102
	v_mul_f32_e32 v102, v109, v119
	v_mul_f32_e32 v102, v102, v103
	v_cvt_pk_bf16_f32 v101, v101, v102
	global_store_dwordx4 v[116:117], v[98:101], off
	ds_bpermute_b32 v98, v180, v183 offset:192
	s_nop 0
	v_or_b32_e32 v99, 48, v181
	v_mad_i64_i32 v[100:101], s[2:3], v99, s49, v[162:163]
	s_waitcnt lgkmcnt(0)
; __device__ __forceinline__ unsigned cvt_pk_bf16(float lo, float hi) { unsigned r; asm volatile("v_cvt_pk_bf16_f32 %0, %1, %2" : "=v"(r) : "v"(lo), "v"(hi)); return r; }
; __device__ __forceinline__ float silu_mul(float a, float b) { return a * b * __builtin_amdgcn_rcpf(1.0f + __builtin_amdgcn_exp2f(-a * LOG2E)); }
; __device__ __forceinline__ float row_rstd(const float* ss, int row) { return 1.0f / sqrtf(ss[row] * (1.0f / DM) + 1e-6f); }
;     __device__ __forceinline__ void operator()(const f32x4 (&acc)[2][2][4][2], const Unit& u, int wr, int wc, int fr, int fq) const {
;     ...
;             for (int m = 0; m < 4; ++m) { const int row = row0 + ai * HALF + m * 16; const float rs = __shfl(ai ? rsl1 : rsl0, m * 16 + fr); bf16_t* rowp = O + (size_t)row * DFF + col0;
;                 const f32x4 a0 = acc[ai][0][m][0] * rs + ba0, a1 = acc[ai][0][m][1] * rs + ba1, b0 = acc[ai][1][m][0] * rs + bb0, b1 = acc[ai][1][m][1] * rs + bb1;
;                 u32x4 w; w.x = cvt_pk_bf16(silu_mul(a0[0], b0[0]), silu_mul(a0[1], b0[1])); w.y = cvt_pk_bf16(silu_mul(a0[2], b0[2]), silu_mul(a0[3], b0[3]));
;                 w.z = cvt_pk_bf16(silu_mul(a1[0], b1[0]), silu_mul(a1[1], b1[1])); w.w = cvt_pk_bf16(silu_mul(a1[2], b1[2]), silu_mul(a1[3], b1[3]));
;                 *(u32x4*)rowp = w; }
	v_fma_f32 v94, v94, v98, v78
	v_fma_f32 v95, v95, v98, v79
	v_fma_f32 v86, v86, v98, v70
	v_fma_f32 v87, v87, v98, v71
	v_fma_f32 v102, v84, v98, v68
	v_fma_f32 v103, v85, v98, v69
	v_fma_f32 v84, v82, v98, v66
	v_fma_f32 v85, v83, v98, v67
	v_mul_f32_e32 v83, 0xbfb8aa3b, v94
	v_mul_f32_e32 v82, v94, v86
	v_exp_f32_e32 v83, v83
	v_mul_f32_e32 v86, 0xbfb8aa3b, v95
	v_exp_f32_e32 v86, v86
	v_fma_f32 v96, v96, v98, v80
	v_fma_f32 v97, v97, v98, v81
	v_add_f32_e32 v83, 1.0, v83
	v_rcp_f32_e32 v83, v83
	v_add_f32_e32 v86, 1.0, v86
	v_rcp_f32_e32 v86, v86
	v_fma_f32 v88, v88, v98, v72
	v_fma_f32 v89, v89, v98, v73
	v_mul_f32_e32 v82, v82, v83
	v_mul_f32_e32 v83, v95, v87
	v_mul_f32_e32 v83, v83, v86
	v_mul_f32_e32 v86, 0xbfb8aa3b, v96
	v_exp_f32_e32 v86, v86
	v_mul_f32_e32 v87, 0xbfb8aa3b, v97
	v_exp_f32_e32 v87, v87
	v_cvt_pk_bf16_f32 v82, v82, v83
	v_add_f32_e32 v86, 1.0, v86
	v_rcp_f32_e32 v86, v86
	v_add_f32_e32 v87, 1.0, v87
	v_rcp_f32_e32 v87, v87
	v_mul_f32_e32 v83, v96, v88
	v_mul_f32_e32 v83, v83, v86
	v_mul_f32_e32 v86, v97, v89
	v_fma_f32 v90, v90, v98, v74
	v_fma_f32 v91, v91, v98, v75
	v_mul_f32_e32 v86, v86, v87
	v_cvt_pk_bf16_f32 v83, v83, v86
	v_mul_f32_e32 v86, 0xbfb8aa3b, v90
	v_exp_f32_e32 v86, v86
	v_mul_f32_e32 v84, v90, v84
	v_fma_f32 v92, v92, v98, v76
	v_fma_f32 v93, v93, v98, v77
	v_mul_f32_e32 v85, v91, v85
	v_add_f32_e32 v86, 1.0, v86
	v_rcp_f32_e32 v86, v86
	v_mul_f32_e32 v87, 0xbfb8aa3b, v93
	v_exp_f32_e32 v87, v87
	v_lshl_add_u64 v[100:101], v[100:101], 0, v[164:165]
	v_mul_f32_e32 v84, v84, v86
	v_mul_f32_e32 v86, 0xbfb8aa3b, v91
	v_exp_f32_e32 v86, v86
	v_add_f32_e32 v87, 1.0, v87
	v_rcp_f32_e32 v87, v87
	v_add_f32_e32 v86, 1.0, v86
	v_rcp_f32_e32 v86, v86
	s_nop 0
	v_mul_f32_e32 v85, v85, v86
	v_mul_f32_e32 v86, 0xbfb8aa3b, v92
	v_exp_f32_e32 v86, v86
	v_cvt_pk_bf16_f32 v84, v84, v85
	v_mul_f32_e32 v85, v92, v102
	v_add_f32_e32 v86, 1.0, v86
	v_rcp_f32_e32 v86, v86
	s_nop 0
	v_mul_f32_e32 v85, v85, v86
	v_mul_f32_e32 v86, v93, v103
	v_mul_f32_e32 v86, v86, v87
	v_cvt_pk_bf16_f32 v85, v85, v86
	global_store_dwordx4 v[100:101], v[82:85], off
	s_nop 1
	v_div_scale_f32 v82, s[2:3], v182, v182, 1.0
	v_rcp_f32_e32 v84, v82
	v_add_u32_e32 v83, 0x80, v181
	v_fma_f32 v85, -v82, v84, 1.0
	v_fmac_f32_e32 v84, v85, v84
	v_div_scale_f32 v85, vcc, 1.0, v182, 1.0
	v_mul_f32_e32 v86, v85, v84
	v_fma_f32 v87, -v82, v86, v85
	v_fmac_f32_e32 v86, v87, v84
	v_fma_f32 v82, -v82, v86, v85
	v_div_fmas_f32 v82, v82, v84, v86
	v_div_fixup_f32 v82, v82, v182, 1.0
	ds_bpermute_b32 v84, v180, v82
	v_mad_i64_i32 v[86:87], s[2:3], v83, s49, v[162:163]
	v_lshl_add_u64 v[86:87], v[86:87], 0, v[164:165]
	s_andn2_b64 vcc, exec, s[38:39]
	s_waitcnt lgkmcnt(0)
	v_fma_f32 v62, v62, v84, v78
	v_fma_f32 v63, v63, v84, v79
	v_fma_f32 v54, v54, v84, v70
	v_fma_f32 v55, v55, v84, v71
	v_fma_f32 v88, v52, v84, v68
	v_fma_f32 v89, v53, v84, v69
	v_fma_f32 v52, v50, v84, v66
	v_fma_f32 v53, v51, v84, v67
	v_mul_f32_e32 v51, 0xbfb8aa3b, v62
	v_mul_f32_e32 v50, v62, v54
	v_exp_f32_e32 v51, v51
	v_mul_f32_e32 v54, 0xbfb8aa3b, v63
	v_exp_f32_e32 v54, v54
	v_fma_f32 v64, v64, v84, v80
	v_fma_f32 v65, v65, v84, v81
	v_add_f32_e32 v51, 1.0, v51
	v_rcp_f32_e32 v51, v51
	v_add_f32_e32 v54, 1.0, v54
	v_rcp_f32_e32 v54, v54
	v_fma_f32 v56, v56, v84, v72
	v_fma_f32 v57, v57, v84, v73
	v_mul_f32_e32 v50, v50, v51
	v_mul_f32_e32 v51, v63, v55
	v_mul_f32_e32 v51, v51, v54
	v_mul_f32_e32 v54, 0xbfb8aa3b, v64
	v_exp_f32_e32 v54, v54
	v_mul_f32_e32 v55, 0xbfb8aa3b, v65
	v_exp_f32_e32 v55, v55
	v_cvt_pk_bf16_f32 v50, v50, v51
	v_add_f32_e32 v54, 1.0, v54
	v_rcp_f32_e32 v54, v54
	v_add_f32_e32 v55, 1.0, v55
	v_rcp_f32_e32 v55, v55
	v_mul_f32_e32 v51, v64, v56
	v_mul_f32_e32 v51, v51, v54
	v_mul_f32_e32 v54, v65, v57
	v_fma_f32 v58, v58, v84, v74
	v_fma_f32 v59, v59, v84, v75
	v_mul_f32_e32 v54, v54, v55
	v_cvt_pk_bf16_f32 v51, v51, v54
	v_mul_f32_e32 v54, 0xbfb8aa3b, v58
	v_exp_f32_e32 v54, v54
	v_mul_f32_e32 v52, v58, v52
	v_fma_f32 v60, v60, v84, v76
	v_fma_f32 v61, v61, v84, v77
	v_mul_f32_e32 v53, v59, v53
	v_add_f32_e32 v54, 1.0, v54
	v_rcp_f32_e32 v54, v54
	v_mul_f32_e32 v55, 0xbfb8aa3b, v61
	v_exp_f32_e32 v55, v55
	v_mul_f32_e32 v52, v52, v54
	v_mul_f32_e32 v54, 0xbfb8aa3b, v59
	v_exp_f32_e32 v54, v54
	v_add_f32_e32 v55, 1.0, v55
	v_rcp_f32_e32 v55, v55
	v_add_f32_e32 v54, 1.0, v54
	v_rcp_f32_e32 v54, v54
	s_nop 0
	v_mul_f32_e32 v53, v53, v54
	v_mul_f32_e32 v54, 0xbfb8aa3b, v60
	v_exp_f32_e32 v54, v54
	v_cvt_pk_bf16_f32 v52, v52, v53
	v_mul_f32_e32 v53, v60, v88
	v_add_f32_e32 v54, 1.0, v54
	v_rcp_f32_e32 v54, v54
	s_nop 0
	v_mul_f32_e32 v53, v53, v54
	v_mul_f32_e32 v54, v61, v89
	v_mul_f32_e32 v54, v54, v55
	v_cvt_pk_bf16_f32 v53, v53, v54
	global_store_dwordx4 v[86:87], v[50:53], off
	ds_bpermute_b32 v50, v180, v82 offset:64
	s_nop 0
	v_add_u32_e32 v51, 0x90, v181
	v_mad_i64_i32 v[52:53], s[2:3], v51, s49, v[162:163]
	s_waitcnt lgkmcnt(0)
; __device__ __forceinline__ unsigned cvt_pk_bf16(float lo, float hi) { unsigned r; asm volatile("v_cvt_pk_bf16_f32 %0, %1, %2" : "=v"(r) : "v"(lo), "v"(hi)); return r; }
; __device__ __forceinline__ float silu_mul(float a, float b) { return a * b * __builtin_amdgcn_rcpf(1.0f + __builtin_amdgcn_exp2f(-a * LOG2E)); }
; #define PG8_BAR __builtin_amdgcn_s_barrier()
;     __device__ __forceinline__ void operator()(const f32x4 (&acc)[2][2][4][2], const Unit& u, int wr, int wc, int fr, int fq) const {
;     ...
;             for (int m = 0; m < 4; ++m) { const int row = row0 + ai * HALF + m * 16; const float rs = __shfl(ai ? rsl1 : rsl0, m * 16 + fr); bf16_t* rowp = O + (size_t)row * DFF + col0;
;                 const f32x4 a0 = acc[ai][0][m][0] * rs + ba0, a1 = acc[ai][0][m][1] * rs + ba1, b0 = acc[ai][1][m][0] * rs + bb0, b1 = acc[ai][1][m][1] * rs + bb1;
;                 u32x4 w; w.x = cvt_pk_bf16(silu_mul(a0[0], b0[0]), silu_mul(a0[1], b0[1])); w.y = cvt_pk_bf16(silu_mul(a0[2], b0[2]), silu_mul(a0[3], b0[3]));
;                 w.z = cvt_pk_bf16(silu_mul(a1[0], b1[0]), silu_mul(a1[1], b1[1])); w.w = cvt_pk_bf16(silu_mul(a1[2], b1[2]), silu_mul(a1[3], b1[3]));
;                 *(u32x4*)rowp = w; }
; template <class Epi, class Sched, bool ALIGN_EPI = false, bool SP2 = false>
; __device__ __forceinline__ void gemm_phase(LAS unsigned char* lds, const Gemm g, const Sched& S, const Epi& E) {
;     ...
;         if constexpr (!Epi::AFTER_DRAIN) { E(acc, cur, wr, wc, fr, fq); S.done(cur); }
;         if (!has_next) break;
; #pragma unroll
;         for (int a = 0; a < 2; ++a)
; #pragma unroll
;             for (int b = 0; b < 2; ++b)
; #pragma unroll
;                 for (int m = 0; m < 4; ++m)
; #pragma unroll
;                     for (int n = 0; n < 2; ++n) acc[a][b][m][n] = (f32x4){0.f, 0.f, 0.f, 0.f};
;         cur = nxt; cA = nA; cB = nB; ++ui;
;         if constexpr (ALIGN_EPI) { if (wr == 1) PG8_BAR; }
	v_fma_f32 v46, v46, v50, v78
	v_fma_f32 v47, v47, v50, v79
	v_fma_f32 v38, v38, v50, v70
	v_fma_f32 v39, v39, v50, v71
	v_fma_f32 v54, v36, v50, v68
	v_fma_f32 v55, v37, v50, v69
	v_fma_f32 v36, v34, v50, v66
	v_fma_f32 v37, v35, v50, v67
	v_mul_f32_e32 v35, 0xbfb8aa3b, v46
	v_mul_f32_e32 v34, v46, v38
	v_exp_f32_e32 v35, v35
	v_mul_f32_e32 v38, 0xbfb8aa3b, v47
	v_exp_f32_e32 v38, v38
	v_fma_f32 v48, v48, v50, v80
	v_fma_f32 v49, v49, v50, v81
	v_add_f32_e32 v35, 1.0, v35
	v_rcp_f32_e32 v35, v35
	v_add_f32_e32 v38, 1.0, v38
	v_rcp_f32_e32 v38, v38
	v_fma_f32 v40, v40, v50, v72
	v_fma_f32 v41, v41, v50, v73
	v_mul_f32_e32 v34, v34, v35
	v_mul_f32_e32 v35, v47, v39
	v_mul_f32_e32 v35, v35, v38
	v_mul_f32_e32 v38, 0xbfb8aa3b, v48
	v_exp_f32_e32 v38, v38
	v_mul_f32_e32 v39, 0xbfb8aa3b, v49
	v_exp_f32_e32 v39, v39
	v_cvt_pk_bf16_f32 v34, v34, v35
	v_add_f32_e32 v38, 1.0, v38
	v_rcp_f32_e32 v38, v38
	v_add_f32_e32 v39, 1.0, v39
	v_rcp_f32_e32 v39, v39
	v_mul_f32_e32 v35, v48, v40
	v_mul_f32_e32 v35, v35, v38
	v_mul_f32_e32 v38, v49, v41
	v_fma_f32 v42, v42, v50, v74
	v_fma_f32 v43, v43, v50, v75
	v_mul_f32_e32 v38, v38, v39
	v_cvt_pk_bf16_f32 v35, v35, v38
	v_mul_f32_e32 v38, 0xbfb8aa3b, v42
	v_exp_f32_e32 v38, v38
	v_mul_f32_e32 v36, v42, v36
	v_fma_f32 v44, v44, v50, v76
	v_fma_f32 v45, v45, v50, v77
	v_mul_f32_e32 v37, v43, v37
	v_add_f32_e32 v38, 1.0, v38
	v_rcp_f32_e32 v38, v38
	v_mul_f32_e32 v39, 0xbfb8aa3b, v45
	v_exp_f32_e32 v39, v39
	v_lshl_add_u64 v[52:53], v[52:53], 0, v[164:165]
	v_mul_f32_e32 v36, v36, v38
	v_mul_f32_e32 v38, 0xbfb8aa3b, v43
	v_exp_f32_e32 v38, v38
	v_add_f32_e32 v39, 1.0, v39
	v_rcp_f32_e32 v39, v39
	v_add_f32_e32 v38, 1.0, v38
	v_rcp_f32_e32 v38, v38
	s_nop 0
	v_mul_f32_e32 v37, v37, v38
	v_mul_f32_e32 v38, 0xbfb8aa3b, v44
	v_exp_f32_e32 v38, v38
	v_cvt_pk_bf16_f32 v36, v36, v37
	v_mul_f32_e32 v37, v44, v54
	v_add_f32_e32 v38, 1.0, v38
	v_rcp_f32_e32 v38, v38
	s_nop 0
	v_mul_f32_e32 v37, v37, v38
	v_mul_f32_e32 v38, v45, v55
	v_mul_f32_e32 v38, v38, v39
	v_cvt_pk_bf16_f32 v37, v37, v38
	global_store_dwordx4 v[52:53], v[34:37], off
	ds_bpermute_b32 v34, v180, v82 offset:128
	s_nop 0
	v_add_u32_e32 v35, 0xa0, v181
	v_mad_i64_i32 v[36:37], s[2:3], v35, s49, v[162:163]
	s_waitcnt lgkmcnt(0)
	v_fma_f32 v30, v30, v34, v78
	v_fma_f32 v31, v31, v34, v79
	v_fma_f32 v22, v22, v34, v70
	v_fma_f32 v23, v23, v34, v71
	v_fma_f32 v38, v20, v34, v68
	v_fma_f32 v39, v21, v34, v69
	v_fma_f32 v20, v18, v34, v66
	v_fma_f32 v21, v19, v34, v67
	v_mul_f32_e32 v19, 0xbfb8aa3b, v30
	v_mul_f32_e32 v18, v30, v22
	v_exp_f32_e32 v19, v19
	v_mul_f32_e32 v22, 0xbfb8aa3b, v31
	v_exp_f32_e32 v22, v22
	v_fma_f32 v32, v32, v34, v80
	v_fma_f32 v33, v33, v34, v81
	v_add_f32_e32 v19, 1.0, v19
	v_rcp_f32_e32 v19, v19
	v_add_f32_e32 v22, 1.0, v22
	v_rcp_f32_e32 v22, v22
	v_fma_f32 v24, v24, v34, v72
	v_fma_f32 v25, v25, v34, v73
	v_mul_f32_e32 v18, v18, v19
	v_mul_f32_e32 v19, v31, v23
	v_mul_f32_e32 v19, v19, v22
	v_mul_f32_e32 v22, 0xbfb8aa3b, v32
	v_exp_f32_e32 v22, v22
	v_mul_f32_e32 v23, 0xbfb8aa3b, v33
	v_exp_f32_e32 v23, v23
	v_cvt_pk_bf16_f32 v18, v18, v19
	v_add_f32_e32 v22, 1.0, v22
	v_rcp_f32_e32 v22, v22
	v_add_f32_e32 v23, 1.0, v23
	v_rcp_f32_e32 v23, v23
	v_mul_f32_e32 v19, v32, v24
	v_mul_f32_e32 v19, v19, v22
	v_mul_f32_e32 v22, v33, v25
	v_fma_f32 v26, v26, v34, v74
	v_fma_f32 v27, v27, v34, v75
	v_mul_f32_e32 v22, v22, v23
	v_cvt_pk_bf16_f32 v19, v19, v22
	v_mul_f32_e32 v22, 0xbfb8aa3b, v26
	v_exp_f32_e32 v22, v22
	v_mul_f32_e32 v20, v26, v20
	v_fma_f32 v28, v28, v34, v76
	v_fma_f32 v29, v29, v34, v77
	v_mul_f32_e32 v21, v27, v21
	v_add_f32_e32 v22, 1.0, v22
	v_rcp_f32_e32 v22, v22
	v_mul_f32_e32 v23, 0xbfb8aa3b, v29
	v_exp_f32_e32 v23, v23
	v_lshl_add_u64 v[36:37], v[36:37], 0, v[164:165]
	v_mul_f32_e32 v20, v20, v22
	v_mul_f32_e32 v22, 0xbfb8aa3b, v27
	v_exp_f32_e32 v22, v22
	v_add_f32_e32 v23, 1.0, v23
	v_rcp_f32_e32 v23, v23
	v_add_f32_e32 v22, 1.0, v22
	v_rcp_f32_e32 v22, v22
	s_nop 0
	v_mul_f32_e32 v21, v21, v22
	v_mul_f32_e32 v22, 0xbfb8aa3b, v28
	v_exp_f32_e32 v22, v22
	v_cvt_pk_bf16_f32 v20, v20, v21
	v_mul_f32_e32 v21, v28, v38
	v_add_f32_e32 v22, 1.0, v22
	v_rcp_f32_e32 v22, v22
	s_nop 0
	v_mul_f32_e32 v21, v21, v22
	v_mul_f32_e32 v22, v29, v39
	v_mul_f32_e32 v22, v22, v23
	v_cvt_pk_bf16_f32 v21, v21, v22
	global_store_dwordx4 v[36:37], v[18:21], off
	ds_bpermute_b32 v18, v180, v82 offset:192
	s_nop 0
	v_add_u32_e32 v19, 0xb0, v181
	v_mad_i64_i32 v[20:21], s[2:3], v19, s49, v[162:163]
	s_waitcnt lgkmcnt(0)
	v_fma_f32 v14, v14, v18, v78
	v_fma_f32 v15, v15, v18, v79
	v_fma_f32 v6, v6, v18, v70
	v_fma_f32 v7, v7, v18, v71
	v_fma_f32 v22, v4, v18, v68
	v_fma_f32 v23, v5, v18, v69
	v_fma_f32 v4, v2, v18, v66
	v_fma_f32 v5, v3, v18, v67
	v_mul_f32_e32 v3, 0xbfb8aa3b, v14
	v_mul_f32_e32 v2, v14, v6
	v_exp_f32_e32 v3, v3
	v_mul_f32_e32 v6, 0xbfb8aa3b, v15
	v_exp_f32_e32 v6, v6
	v_fma_f32 v16, v16, v18, v80
	v_fma_f32 v17, v17, v18, v81
	v_add_f32_e32 v3, 1.0, v3
	v_rcp_f32_e32 v3, v3
	v_add_f32_e32 v6, 1.0, v6
	v_rcp_f32_e32 v6, v6
	v_fma_f32 v8, v8, v18, v72
	v_fma_f32 v9, v9, v18, v73
	v_mul_f32_e32 v2, v2, v3
	v_mul_f32_e32 v3, v15, v7
	v_mul_f32_e32 v3, v3, v6
	v_mul_f32_e32 v6, 0xbfb8aa3b, v16
	v_exp_f32_e32 v6, v6
	v_mul_f32_e32 v7, 0xbfb8aa3b, v17
	v_exp_f32_e32 v7, v7
	v_cvt_pk_bf16_f32 v2, v2, v3
	v_add_f32_e32 v6, 1.0, v6
	v_rcp_f32_e32 v6, v6
	v_add_f32_e32 v7, 1.0, v7
	v_rcp_f32_e32 v7, v7
	v_mul_f32_e32 v3, v16, v8
	v_mul_f32_e32 v3, v3, v6
	v_mul_f32_e32 v6, v17, v9
	v_fma_f32 v10, v10, v18, v74
	v_fma_f32 v11, v11, v18, v75
	v_mul_f32_e32 v6, v6, v7
	v_cvt_pk_bf16_f32 v3, v3, v6
	v_mul_f32_e32 v6, 0xbfb8aa3b, v10
	v_exp_f32_e32 v6, v6
	v_mul_f32_e32 v4, v10, v4
	v_fma_f32 v12, v12, v18, v76
	v_fma_f32 v13, v13, v18, v77
	v_mul_f32_e32 v5, v11, v5
	v_add_f32_e32 v6, 1.0, v6
	v_rcp_f32_e32 v6, v6
	v_mul_f32_e32 v7, 0xbfb8aa3b, v13
	v_exp_f32_e32 v7, v7
	v_lshl_add_u64 v[20:21], v[20:21], 0, v[164:165]
	v_mul_f32_e32 v4, v4, v6
	v_mul_f32_e32 v6, 0xbfb8aa3b, v11
	v_exp_f32_e32 v6, v6
	v_add_f32_e32 v7, 1.0, v7
	v_rcp_f32_e32 v7, v7
	s_mov_b64 s[2:3], -1
	v_add_f32_e32 v6, 1.0, v6
	v_rcp_f32_e32 v6, v6
	s_nop 0
	v_mul_f32_e32 v5, v5, v6
	v_mul_f32_e32 v6, 0xbfb8aa3b, v12
	v_exp_f32_e32 v6, v6
	v_cvt_pk_bf16_f32 v4, v4, v5
	v_mul_f32_e32 v5, v12, v22
	v_add_f32_e32 v6, 1.0, v6
	v_rcp_f32_e32 v6, v6
	s_nop 0
	v_mul_f32_e32 v5, v5, v6
	v_mul_f32_e32 v6, v13, v23
	v_mul_f32_e32 v6, v6, v7
	v_cvt_pk_bf16_f32 v5, v5, v6
	global_store_dwordx4 v[20:21], v[2:5], off
	s_cbranch_vccnz .LBB0_1461
	s_andn2_b64 vcc, exec, s[4:5]
	s_cbranch_vccnz .LBB0_1460
	s_barrier
	s_branch .LBB0_1460

; __device__ __forceinline__ unsigned cvt_pk_bf16(float lo, float hi) { unsigned r; asm volatile("v_cvt_pk_bf16_f32 %0, %1, %2" : "=v"(r) : "v"(lo), "v"(hi)); return r; }
; __device__ __forceinline__ float silu_mul(float a, float b) { return a * b * __builtin_amdgcn_rcpf(1.0f + __builtin_amdgcn_exp2f(-a * LOG2E)); }
; __device__ __forceinline__ float row_rstd(const float* ss, int row) { return 1.0f / sqrtf(ss[row] * (1.0f / DM) + 1e-6f); }
;     __device__ __forceinline__ void operator()(const f32x4 (&acc)[2][2][4][2], const Unit& u, int wr, int wc, int fr, int fq) const {
;         const int row0 = u.pm * BM + wr * 64 + fr, col0 = u.pn * HALF + wc * 32 + 8 * fq;
;         const int s = (u.pm < ML / BM) ? (u.pm >> 5) : 4;
;         const float* bp = bias + (size_t)s * BIAS_N + u.pn * BM + wc * 32 + 8 * fq;
;         const f32x4 ba0 = *(const f32x4*)bp, ba1 = *(const f32x4*)(bp + 4), bb0 = *(const f32x4*)(bp + HALF), bb1 = *(const f32x4*)(bp + HALF + 4);
;         const int lane = fq * 16 + fr;
;         const float rsl0 = row_rstd(ss, u.pm * BM + wr * 64 + lane), rsl1 = row_rstd(ss, u.pm * BM + HALF + wr * 64 + lane);
; #pragma unroll
;         for (int ai = 0; ai < 2; ++ai)
; #pragma unroll
;             for (int m = 0; m < 4; ++m) { const int row = row0 + ai * HALF + m * 16; const float rs = __shfl(ai ? rsl1 : rsl0, m * 16 + fr); bf16_t* rowp = O + (size_t)row * DFF + col0;
;                 const f32x4 a0 = acc[ai][0][m][0] * rs + ba0, a1 = acc[ai][0][m][1] * rs + ba1, b0 = acc[ai][1][m][0] * rs + bb0, b1 = acc[ai][1][m][1] * rs + bb1;
;                 u32x4 w; w.x = cvt_pk_bf16(silu_mul(a0[0], b0[0]), silu_mul(a0[1], b0[1])); w.y = cvt_pk_bf16(silu_mul(a0[2], b0[2]), silu_mul(a0[3], b0[3]));
;                 w.z = cvt_pk_bf16(silu_mul(a1[0], b1[0]), silu_mul(a1[1], b1[1])); w.w = cvt_pk_bf16(silu_mul(a1[2], b1[2]), silu_mul(a1[3], b1[3]));
;                 *(u32x4*)rowp = w; }
.LBB0_1827:
	s_lshl_b32 s2, s2, 8
	s_add_i32 s13, s2, s35
	s_lshl_b64 s[2:3], s[16:17], 2
	s_add_u32 s15, s36, s2
	s_addc_u32 s16, s37, s3
	s_lshl_b32 s2, s0, 8
	s_ashr_i32 s3, s2, 31
	s_lshl_b64 s[2:3], s[2:3], 2
	v_lshl_or_b32 v164, s0, 7, v172
	s_add_u32 s0, s15, s2
	s_addc_u32 s3, s16, s3
	v_or_b32_e32 v162, s13, v170
	s_add_u32 s2, s0, s47
	v_ashrrev_i32_e32 v163, 31, v162
	s_addc_u32 s3, s3, 0
	v_lshl_add_u64 v[162:163], v[162:163], 2, s[6:7]
	v_mov_b32_e32 v74, v234
	v_mov_b32_e32 v75, v235
	v_mov_b32_e32 v76, v236
	v_mov_b32_e32 v77, v237
	v_mov_b32_e32 v78, v238
	v_mov_b32_e32 v79, v239
	v_mov_b32_e32 v80, v240
	v_mov_b32_e32 v81, v241
	v_mov_b32_e32 v66, v242
	v_mov_b32_e32 v67, v243
	v_mov_b32_e32 v68, v244
	v_mov_b32_e32 v69, v245
	v_mov_b32_e32 v70, v246
	v_mov_b32_e32 v71, v247
	v_mov_b32_e32 v72, v248
	v_mov_b32_e32 v73, v249
	v_or_b32_e32 v180, s13, v1
	v_mov_b32_e32 v162, v250
	s_waitcnt vmcnt(0)
	v_fmamk_f32 v162, v162, 0x3a000000, v177
	v_cmp_gt_f32_e32 vcc, s48, v162
	v_mul_f32_e32 v163, 0x4f800000, v162
	s_nop 0
	v_cndmask_b32_e32 v162, v162, v163, vcc
	v_sqrt_f32_e32 v163, v162
	s_nop 0
	v_add_u32_e32 v165, -1, v163
	v_fma_f32 v166, -v165, v163, v162
	v_cmp_ge_f32_e64 s[2:3], 0, v166
	v_add_u32_e32 v166, 1, v163
	s_nop 0
	v_cndmask_b32_e64 v165, v163, v165, s[2:3]
	v_fma_f32 v163, -v166, v163, v162
	v_cmp_lt_f32_e64 s[2:3], 0, v163
	s_nop 1
	v_cndmask_b32_e64 v163, v165, v166, s[2:3]
	v_mul_f32_e32 v165, 0x37800000, v163
	v_cndmask_b32_e32 v163, v163, v165, vcc
	v_cmp_class_f32_e32 vcc, v162, v178
	s_nop 1
	v_cndmask_b32_e32 v166, v163, v162, vcc
	v_add_u32_e32 v162, s13, v171
	v_ashrrev_i32_e32 v163, 31, v162
	v_lshl_add_u64 v[162:163], v[162:163], 2, s[6:7]
	v_mov_b32_e32 v162, v251
	v_fmamk_f32 v162, v162, 0x3a000000, v177
	v_cmp_gt_f32_e32 vcc, s48, v162
	v_mul_f32_e32 v163, 0x4f800000, v162
	s_nop 0
	v_cndmask_b32_e32 v162, v162, v163, vcc
	v_sqrt_f32_e32 v163, v162
	s_nop 0
	v_add_u32_e32 v165, -1, v163
	v_fma_f32 v167, -v165, v163, v162
	v_cmp_ge_f32_e64 s[2:3], 0, v167
	v_add_u32_e32 v167, 1, v163
	s_nop 0
	v_cndmask_b32_e64 v165, v163, v165, s[2:3]
	v_fma_f32 v163, -v167, v163, v162
	v_cmp_lt_f32_e64 s[2:3], 0, v163
	s_nop 1
	v_cndmask_b32_e64 v163, v165, v167, s[2:3]
	v_mul_f32_e32 v165, 0x37800000, v163
	v_cndmask_b32_e32 v163, v163, v165, vcc
	v_cmp_class_f32_e32 vcc, v162, v178
	v_ashrrev_i32_e32 v165, 31, v164
	v_lshlrev_b64 v[164:165], 1, v[164:165]
	v_cndmask_b32_e32 v181, v163, v162, vcc
	v_div_scale_f32 v162, s[2:3], v166, v166, 1.0
	v_rcp_f32_e32 v163, v162
	s_nop 0
	v_fma_f32 v167, -v162, v163, 1.0
	v_fmac_f32_e32 v163, v167, v163
	v_div_scale_f32 v167, vcc, 1.0, v166, 1.0
	v_mul_f32_e32 v168, v167, v163
	v_fma_f32 v182, -v162, v168, v167
	v_fmac_f32_e32 v168, v182, v163
	v_fma_f32 v162, -v162, v168, v167
	v_div_fmas_f32 v162, v162, v163, v168
	v_div_fixup_f32 v182, v162, v166, 1.0
	ds_bpermute_b32 v168, v179, v182
	v_mov_b64_e32 v[162:163], s[96:97]
	v_mad_i64_i32 v[166:167], s[2:3], v180, s46, v[162:163]
	v_lshl_add_u64 v[166:167], v[166:167], 0, v[164:165]
	s_waitcnt lgkmcnt(0)
	v_fma_f32 v142, v142, v168, v78
	v_fma_f32 v143, v143, v168, v79
	v_fma_f32 v134, v134, v168, v70
	v_fma_f32 v135, v135, v168, v71
	v_fma_f32 v184, v132, v168, v68
	v_fma_f32 v185, v133, v168, v69
	v_fma_f32 v132, v130, v168, v66
	v_fma_f32 v133, v131, v168, v67
	v_mul_f32_e32 v131, 0xbfb8aa3b, v142
	v_mul_f32_e32 v130, v142, v134
	v_exp_f32_e32 v131, v131
	v_mul_f32_e32 v134, 0xbfb8aa3b, v143
	v_exp_f32_e32 v134, v134
	v_fma_f32 v144, v144, v168, v80
	v_fma_f32 v145, v145, v168, v81
	v_add_f32_e32 v131, 1.0, v131
	v_rcp_f32_e32 v131, v131
	v_add_f32_e32 v134, 1.0, v134
	v_rcp_f32_e32 v134, v134
	v_fma_f32 v136, v136, v168, v72
	v_fma_f32 v137, v137, v168, v73
	v_mul_f32_e32 v130, v130, v131
	v_mul_f32_e32 v131, v143, v135
	v_mul_f32_e32 v131, v131, v134
	v_mul_f32_e32 v134, 0xbfb8aa3b, v144
	v_exp_f32_e32 v134, v134
	v_mul_f32_e32 v135, 0xbfb8aa3b, v145
	v_exp_f32_e32 v135, v135
	v_cvt_pk_bf16_f32 v130, v130, v131
	v_add_f32_e32 v134, 1.0, v134
	v_rcp_f32_e32 v134, v134
	v_add_f32_e32 v135, 1.0, v135
	v_rcp_f32_e32 v135, v135
	v_mul_f32_e32 v131, v144, v136
	v_mul_f32_e32 v131, v131, v134
	v_mul_f32_e32 v134, v145, v137
	v_fma_f32 v138, v138, v168, v74
	v_fma_f32 v139, v139, v168, v75
	v_mul_f32_e32 v134, v134, v135
	v_cvt_pk_bf16_f32 v131, v131, v134
	v_mul_f32_e32 v134, 0xbfb8aa3b, v138
	v_exp_f32_e32 v134, v134
	v_mul_f32_e32 v132, v138, v132
	v_fma_f32 v140, v140, v168, v76
	v_fma_f32 v141, v141, v168, v77
	v_mul_f32_e32 v133, v139, v133
	v_add_f32_e32 v134, 1.0, v134
	v_rcp_f32_e32 v134, v134
	v_mul_f32_e32 v135, 0xbfb8aa3b, v141
	v_exp_f32_e32 v135, v135
	v_mul_f32_e32 v132, v132, v134
	v_mul_f32_e32 v134, 0xbfb8aa3b, v139
	v_exp_f32_e32 v134, v134
	v_add_f32_e32 v135, 1.0, v135
	v_rcp_f32_e32 v135, v135
	v_add_f32_e32 v134, 1.0, v134
	v_rcp_f32_e32 v134, v134
	s_nop 0
	v_mul_f32_e32 v133, v133, v134
	v_mul_f32_e32 v134, 0xbfb8aa3b, v140
	v_exp_f32_e32 v134, v134
	v_cvt_pk_bf16_f32 v132, v132, v133
	v_mul_f32_e32 v133, v140, v184
	v_add_f32_e32 v134, 1.0, v134
	v_rcp_f32_e32 v134, v134
	s_nop 0
	v_mul_f32_e32 v133, v133, v134
	v_mul_f32_e32 v134, v141, v185
	v_mul_f32_e32 v134, v134, v135
	v_cvt_pk_bf16_f32 v133, v133, v134
	global_store_dwordx4 v[166:167], v[130:133], off
	ds_bpermute_b32 v130, v179, v182 offset:64
	s_nop 0
	v_or_b32_e32 v131, 16, v180
	v_mad_i64_i32 v[132:133], s[2:3], v131, s46, v[162:163]
	s_waitcnt lgkmcnt(0)
; __device__ __forceinline__ unsigned cvt_pk_bf16(float lo, float hi) { unsigned r; asm volatile("v_cvt_pk_bf16_f32 %0, %1, %2" : "=v"(r) : "v"(lo), "v"(hi)); return r; }
; __device__ __forceinline__ float silu_mul(float a, float b) { return a * b * __builtin_amdgcn_rcpf(1.0f + __builtin_amdgcn_exp2f(-a * LOG2E)); }
;     __device__ __forceinline__ void operator()(const f32x4 (&acc)[2][2][4][2], const Unit& u, int wr, int wc, int fr, int fq) const {
;     ...
;             for (int m = 0; m < 4; ++m) { const int row = row0 + ai * HALF + m * 16; const float rs = __shfl(ai ? rsl1 : rsl0, m * 16 + fr); bf16_t* rowp = O + (size_t)row * DFF + col0;
;                 const f32x4 a0 = acc[ai][0][m][0] * rs + ba0, a1 = acc[ai][0][m][1] * rs + ba1, b0 = acc[ai][1][m][0] * rs + bb0, b1 = acc[ai][1][m][1] * rs + bb1;
;                 u32x4 w; w.x = cvt_pk_bf16(silu_mul(a0[0], b0[0]), silu_mul(a0[1], b0[1])); w.y = cvt_pk_bf16(silu_mul(a0[2], b0[2]), silu_mul(a0[3], b0[3]));
;                 w.z = cvt_pk_bf16(silu_mul(a1[0], b1[0]), silu_mul(a1[1], b1[1])); w.w = cvt_pk_bf16(silu_mul(a1[2], b1[2]), silu_mul(a1[3], b1[3]));
;                 *(u32x4*)rowp = w; }
	v_fma_f32 v126, v126, v130, v78
	v_fma_f32 v127, v127, v130, v79
	v_fma_f32 v118, v118, v130, v70
	v_fma_f32 v119, v119, v130, v71
	v_fma_f32 v134, v116, v130, v68
	v_fma_f32 v135, v117, v130, v69
	v_fma_f32 v116, v114, v130, v66
	v_fma_f32 v117, v115, v130, v67
	v_mul_f32_e32 v115, 0xbfb8aa3b, v126
	v_mul_f32_e32 v114, v126, v118
	v_exp_f32_e32 v115, v115
	v_mul_f32_e32 v118, 0xbfb8aa3b, v127
	v_exp_f32_e32 v118, v118
	v_fma_f32 v128, v128, v130, v80
	v_fma_f32 v129, v129, v130, v81
	v_add_f32_e32 v115, 1.0, v115
	v_rcp_f32_e32 v115, v115
	v_add_f32_e32 v118, 1.0, v118
	v_rcp_f32_e32 v118, v118
	v_fma_f32 v120, v120, v130, v72
	v_fma_f32 v121, v121, v130, v73
	v_mul_f32_e32 v114, v114, v115
	v_mul_f32_e32 v115, v127, v119
	v_mul_f32_e32 v115, v115, v118
	v_mul_f32_e32 v118, 0xbfb8aa3b, v128
	v_exp_f32_e32 v118, v118
	v_mul_f32_e32 v119, 0xbfb8aa3b, v129
	v_exp_f32_e32 v119, v119
	v_cvt_pk_bf16_f32 v114, v114, v115
	v_add_f32_e32 v118, 1.0, v118
	v_rcp_f32_e32 v118, v118
	v_add_f32_e32 v119, 1.0, v119
	v_rcp_f32_e32 v119, v119
	v_mul_f32_e32 v115, v128, v120
	v_mul_f32_e32 v115, v115, v118
	v_mul_f32_e32 v118, v129, v121
	v_fma_f32 v122, v122, v130, v74
	v_fma_f32 v123, v123, v130, v75
	v_mul_f32_e32 v118, v118, v119
	v_cvt_pk_bf16_f32 v115, v115, v118
	v_mul_f32_e32 v118, 0xbfb8aa3b, v122
	v_exp_f32_e32 v118, v118
	v_mul_f32_e32 v116, v122, v116
	v_fma_f32 v124, v124, v130, v76
	v_fma_f32 v125, v125, v130, v77
	v_mul_f32_e32 v117, v123, v117
	v_add_f32_e32 v118, 1.0, v118
	v_rcp_f32_e32 v118, v118
	v_mul_f32_e32 v119, 0xbfb8aa3b, v125
	v_exp_f32_e32 v119, v119
	v_lshl_add_u64 v[132:133], v[132:133], 0, v[164:165]
	v_mul_f32_e32 v116, v116, v118
	v_mul_f32_e32 v118, 0xbfb8aa3b, v123
	v_exp_f32_e32 v118, v118
	v_add_f32_e32 v119, 1.0, v119
	v_rcp_f32_e32 v119, v119
	v_add_f32_e32 v118, 1.0, v118
	v_rcp_f32_e32 v118, v118
	s_nop 0
	v_mul_f32_e32 v117, v117, v118
	v_mul_f32_e32 v118, 0xbfb8aa3b, v124
	v_exp_f32_e32 v118, v118
	v_cvt_pk_bf16_f32 v116, v116, v117
	v_mul_f32_e32 v117, v124, v134
	v_add_f32_e32 v118, 1.0, v118
	v_rcp_f32_e32 v118, v118
	s_nop 0
	v_mul_f32_e32 v117, v117, v118
	v_mul_f32_e32 v118, v125, v135
	v_mul_f32_e32 v118, v118, v119
	v_cvt_pk_bf16_f32 v117, v117, v118
	global_store_dwordx4 v[132:133], v[114:117], off
	ds_bpermute_b32 v114, v179, v182 offset:128
	s_nop 0
	v_or_b32_e32 v115, 32, v180
	v_mad_i64_i32 v[116:117], s[2:3], v115, s46, v[162:163]
	s_waitcnt lgkmcnt(0)
	v_fma_f32 v110, v110, v114, v78
	v_fma_f32 v111, v111, v114, v79
	v_fma_f32 v102, v102, v114, v70
	v_fma_f32 v103, v103, v114, v71
	v_fma_f32 v118, v100, v114, v68
	v_fma_f32 v119, v101, v114, v69
	v_fma_f32 v100, v98, v114, v66
	v_fma_f32 v101, v99, v114, v67
	v_mul_f32_e32 v99, 0xbfb8aa3b, v110
	v_mul_f32_e32 v98, v110, v102
	v_exp_f32_e32 v99, v99
	v_mul_f32_e32 v102, 0xbfb8aa3b, v111
	v_exp_f32_e32 v102, v102
	v_fma_f32 v112, v112, v114, v80
	v_fma_f32 v113, v113, v114, v81
	v_add_f32_e32 v99, 1.0, v99
	v_rcp_f32_e32 v99, v99
	v_add_f32_e32 v102, 1.0, v102
	v_rcp_f32_e32 v102, v102
	v_fma_f32 v104, v104, v114, v72
	v_fma_f32 v105, v105, v114, v73
	v_mul_f32_e32 v98, v98, v99
	v_mul_f32_e32 v99, v111, v103
	v_mul_f32_e32 v99, v99, v102
	v_mul_f32_e32 v102, 0xbfb8aa3b, v112
	v_exp_f32_e32 v102, v102
	v_mul_f32_e32 v103, 0xbfb8aa3b, v113
	v_exp_f32_e32 v103, v103
	v_cvt_pk_bf16_f32 v98, v98, v99
	v_add_f32_e32 v102, 1.0, v102
	v_rcp_f32_e32 v102, v102
	v_add_f32_e32 v103, 1.0, v103
	v_rcp_f32_e32 v103, v103
	v_mul_f32_e32 v99, v112, v104
	v_mul_f32_e32 v99, v99, v102
	v_mul_f32_e32 v102, v113, v105
	v_fma_f32 v106, v106, v114, v74
	v_fma_f32 v107, v107, v114, v75
	v_mul_f32_e32 v102, v102, v103
	v_cvt_pk_bf16_f32 v99, v99, v102
	v_mul_f32_e32 v102, 0xbfb8aa3b, v106
	v_exp_f32_e32 v102, v102
	v_mul_f32_e32 v100, v106, v100
	v_fma_f32 v108, v108, v114, v76
	v_fma_f32 v109, v109, v114, v77
	v_mul_f32_e32 v101, v107, v101
	v_add_f32_e32 v102, 1.0, v102
	v_rcp_f32_e32 v102, v102
	v_mul_f32_e32 v103, 0xbfb8aa3b, v109
	v_exp_f32_e32 v103, v103
	v_lshl_add_u64 v[116:117], v[116:117], 0, v[164:165]
	v_mul_f32_e32 v100, v100, v102
	v_mul_f32_e32 v102, 0xbfb8aa3b, v107
	v_exp_f32_e32 v102, v102
	v_add_f32_e32 v103, 1.0, v103
	v_rcp_f32_e32 v103, v103
	v_add_f32_e32 v102, 1.0, v102
	v_rcp_f32_e32 v102, v102
	s_nop 0
	v_mul_f32_e32 v101, v101, v102
	v_mul_f32_e32 v102, 0xbfb8aa3b, v108
	v_exp_f32_e32 v102, v102
	v_cvt_pk_bf16_f32 v100, v100, v101
	v_mul_f32_e32 v101, v108, v118
	v_add_f32_e32 v102, 1.0, v102
	v_rcp_f32_e32 v102, v102
	s_nop 0
	v_mul_f32_e32 v101, v101, v102
	v_mul_f32_e32 v102, v109, v119
	v_mul_f32_e32 v102, v102, v103
	v_cvt_pk_bf16_f32 v101, v101, v102
	global_store_dwordx4 v[116:117], v[98:101], off
	ds_bpermute_b32 v98, v179, v182 offset:192
	s_nop 0
	v_or_b32_e32 v99, 48, v180
	v_mad_i64_i32 v[100:101], s[2:3], v99, s46, v[162:163]
	s_waitcnt lgkmcnt(0)
; __device__ __forceinline__ unsigned cvt_pk_bf16(float lo, float hi) { unsigned r; asm volatile("v_cvt_pk_bf16_f32 %0, %1, %2" : "=v"(r) : "v"(lo), "v"(hi)); return r; }
; __device__ __forceinline__ float silu_mul(float a, float b) { return a * b * __builtin_amdgcn_rcpf(1.0f + __builtin_amdgcn_exp2f(-a * LOG2E)); }
; __device__ __forceinline__ float row_rstd(const float* ss, int row) { return 1.0f / sqrtf(ss[row] * (1.0f / DM) + 1e-6f); }
;     __device__ __forceinline__ void operator()(const f32x4 (&acc)[2][2][4][2], const Unit& u, int wr, int wc, int fr, int fq) const {
;     ...
;             for (int m = 0; m < 4; ++m) { const int row = row0 + ai * HALF + m * 16; const float rs = __shfl(ai ? rsl1 : rsl0, m * 16 + fr); bf16_t* rowp = O + (size_t)row * DFF + col0;
;                 const f32x4 a0 = acc[ai][0][m][0] * rs + ba0, a1 = acc[ai][0][m][1] * rs + ba1, b0 = acc[ai][1][m][0] * rs + bb0, b1 = acc[ai][1][m][1] * rs + bb1;
;                 u32x4 w; w.x = cvt_pk_bf16(silu_mul(a0[0], b0[0]), silu_mul(a0[1], b0[1])); w.y = cvt_pk_bf16(silu_mul(a0[2], b0[2]), silu_mul(a0[3], b0[3]));
;                 w.z = cvt_pk_bf16(silu_mul(a1[0], b1[0]), silu_mul(a1[1], b1[1])); w.w = cvt_pk_bf16(silu_mul(a1[2], b1[2]), silu_mul(a1[3], b1[3]));
;                 *(u32x4*)rowp = w; }
	v_fma_f32 v94, v94, v98, v78
	v_fma_f32 v95, v95, v98, v79
	v_fma_f32 v86, v86, v98, v70
	v_fma_f32 v87, v87, v98, v71
	v_fma_f32 v102, v84, v98, v68
	v_fma_f32 v103, v85, v98, v69
	v_fma_f32 v84, v82, v98, v66
	v_fma_f32 v85, v83, v98, v67
	v_mul_f32_e32 v83, 0xbfb8aa3b, v94
	v_mul_f32_e32 v82, v94, v86
	v_exp_f32_e32 v83, v83
	v_mul_f32_e32 v86, 0xbfb8aa3b, v95
	v_exp_f32_e32 v86, v86
	v_fma_f32 v96, v96, v98, v80
	v_fma_f32 v97, v97, v98, v81
	v_add_f32_e32 v83, 1.0, v83
	v_rcp_f32_e32 v83, v83
	v_add_f32_e32 v86, 1.0, v86
	v_rcp_f32_e32 v86, v86
	v_fma_f32 v88, v88, v98, v72
	v_fma_f32 v89, v89, v98, v73
	v_mul_f32_e32 v82, v82, v83
	v_mul_f32_e32 v83, v95, v87
	v_mul_f32_e32 v83, v83, v86
	v_mul_f32_e32 v86, 0xbfb8aa3b, v96
	v_exp_f32_e32 v86, v86
	v_mul_f32_e32 v87, 0xbfb8aa3b, v97
	v_exp_f32_e32 v87, v87
	v_cvt_pk_bf16_f32 v82, v82, v83
	v_add_f32_e32 v86, 1.0, v86
	v_rcp_f32_e32 v86, v86
	v_add_f32_e32 v87, 1.0, v87
	v_rcp_f32_e32 v87, v87
	v_mul_f32_e32 v83, v96, v88
	v_mul_f32_e32 v83, v83, v86
	v_mul_f32_e32 v86, v97, v89
	v_fma_f32 v90, v90, v98, v74
	v_fma_f32 v91, v91, v98, v75
	v_mul_f32_e32 v86, v86, v87
	v_cvt_pk_bf16_f32 v83, v83, v86
	v_mul_f32_e32 v86, 0xbfb8aa3b, v90
	v_exp_f32_e32 v86, v86
	v_mul_f32_e32 v84, v90, v84
	v_fma_f32 v92, v92, v98, v76
	v_fma_f32 v93, v93, v98, v77
	v_mul_f32_e32 v85, v91, v85
	v_add_f32_e32 v86, 1.0, v86
	v_rcp_f32_e32 v86, v86
	v_mul_f32_e32 v87, 0xbfb8aa3b, v93
	v_exp_f32_e32 v87, v87
	v_lshl_add_u64 v[100:101], v[100:101], 0, v[164:165]
	v_mul_f32_e32 v84, v84, v86
	v_mul_f32_e32 v86, 0xbfb8aa3b, v91
	v_exp_f32_e32 v86, v86
	v_add_f32_e32 v87, 1.0, v87
	v_rcp_f32_e32 v87, v87
	v_add_f32_e32 v86, 1.0, v86
	v_rcp_f32_e32 v86, v86
	s_nop 0
	v_mul_f32_e32 v85, v85, v86
	v_mul_f32_e32 v86, 0xbfb8aa3b, v92
	v_exp_f32_e32 v86, v86
	v_cvt_pk_bf16_f32 v84, v84, v85
	v_mul_f32_e32 v85, v92, v102
	v_add_f32_e32 v86, 1.0, v86
	v_rcp_f32_e32 v86, v86
	s_nop 0
	v_mul_f32_e32 v85, v85, v86
	v_mul_f32_e32 v86, v93, v103
	v_mul_f32_e32 v86, v86, v87
	v_cvt_pk_bf16_f32 v85, v85, v86
	global_store_dwordx4 v[100:101], v[82:85], off
	s_nop 1
	v_div_scale_f32 v82, s[2:3], v181, v181, 1.0
	v_rcp_f32_e32 v84, v82
	v_add_u32_e32 v83, 0x80, v180
	v_fma_f32 v85, -v82, v84, 1.0
	v_fmac_f32_e32 v84, v85, v84
	v_div_scale_f32 v85, vcc, 1.0, v181, 1.0
	v_mul_f32_e32 v86, v85, v84
	v_fma_f32 v87, -v82, v86, v85
	v_fmac_f32_e32 v86, v87, v84
	v_fma_f32 v82, -v82, v86, v85
	v_div_fmas_f32 v82, v82, v84, v86
	v_div_fixup_f32 v82, v82, v181, 1.0
	ds_bpermute_b32 v84, v179, v82
	v_mad_i64_i32 v[86:87], s[2:3], v83, s46, v[162:163]
	v_lshl_add_u64 v[86:87], v[86:87], 0, v[164:165]
	s_and_b64 vcc, s[38:39], exec
	s_waitcnt lgkmcnt(0)
	v_fma_f32 v62, v62, v84, v78
	v_fma_f32 v63, v63, v84, v79
	v_fma_f32 v54, v54, v84, v70
	v_fma_f32 v55, v55, v84, v71
	v_fma_f32 v88, v52, v84, v68
	v_fma_f32 v89, v53, v84, v69
	v_fma_f32 v52, v50, v84, v66
	v_fma_f32 v53, v51, v84, v67
	v_mul_f32_e32 v51, 0xbfb8aa3b, v62
	v_mul_f32_e32 v50, v62, v54
	v_exp_f32_e32 v51, v51
	v_mul_f32_e32 v54, 0xbfb8aa3b, v63
	v_exp_f32_e32 v54, v54
	v_fma_f32 v64, v64, v84, v80
	v_fma_f32 v65, v65, v84, v81
	v_add_f32_e32 v51, 1.0, v51
	v_rcp_f32_e32 v51, v51
	v_add_f32_e32 v54, 1.0, v54
	v_rcp_f32_e32 v54, v54
	v_fma_f32 v56, v56, v84, v72
	v_fma_f32 v57, v57, v84, v73
	v_mul_f32_e32 v50, v50, v51
	v_mul_f32_e32 v51, v63, v55
	v_mul_f32_e32 v51, v51, v54
	v_mul_f32_e32 v54, 0xbfb8aa3b, v64
	v_exp_f32_e32 v54, v54
	v_mul_f32_e32 v55, 0xbfb8aa3b, v65
	v_exp_f32_e32 v55, v55
	v_cvt_pk_bf16_f32 v50, v50, v51
	v_add_f32_e32 v54, 1.0, v54
	v_rcp_f32_e32 v54, v54
	v_add_f32_e32 v55, 1.0, v55
	v_rcp_f32_e32 v55, v55
	v_mul_f32_e32 v51, v64, v56
	v_mul_f32_e32 v51, v51, v54
	v_mul_f32_e32 v54, v65, v57
	v_fma_f32 v58, v58, v84, v74
	v_fma_f32 v59, v59, v84, v75
	v_mul_f32_e32 v54, v54, v55
	v_cvt_pk_bf16_f32 v51, v51, v54
	v_mul_f32_e32 v54, 0xbfb8aa3b, v58
	v_exp_f32_e32 v54, v54
	v_mul_f32_e32 v52, v58, v52
	v_fma_f32 v60, v60, v84, v76
	v_fma_f32 v61, v61, v84, v77
	v_mul_f32_e32 v53, v59, v53
	v_add_f32_e32 v54, 1.0, v54
	v_rcp_f32_e32 v54, v54
	v_mul_f32_e32 v55, 0xbfb8aa3b, v61
	v_exp_f32_e32 v55, v55
	v_mul_f32_e32 v52, v52, v54
	v_mul_f32_e32 v54, 0xbfb8aa3b, v59
	v_exp_f32_e32 v54, v54
	v_add_f32_e32 v55, 1.0, v55
	v_rcp_f32_e32 v55, v55
	v_add_f32_e32 v54, 1.0, v54
	v_rcp_f32_e32 v54, v54
	s_nop 0
	v_mul_f32_e32 v53, v53, v54
	v_mul_f32_e32 v54, 0xbfb8aa3b, v60
	v_exp_f32_e32 v54, v54
	v_cvt_pk_bf16_f32 v52, v52, v53
	v_mul_f32_e32 v53, v60, v88
	v_add_f32_e32 v54, 1.0, v54
	v_rcp_f32_e32 v54, v54
	s_nop 0
	v_mul_f32_e32 v53, v53, v54
	v_mul_f32_e32 v54, v61, v89
	v_mul_f32_e32 v54, v54, v55
	v_cvt_pk_bf16_f32 v53, v53, v54
	global_store_dwordx4 v[86:87], v[50:53], off
	ds_bpermute_b32 v50, v179, v82 offset:64
	s_nop 0
	v_add_u32_e32 v51, 0x90, v180
	v_mad_i64_i32 v[52:53], s[2:3], v51, s46, v[162:163]
	s_waitcnt lgkmcnt(0)
; __device__ __forceinline__ unsigned cvt_pk_bf16(float lo, float hi) { unsigned r; asm volatile("v_cvt_pk_bf16_f32 %0, %1, %2" : "=v"(r) : "v"(lo), "v"(hi)); return r; }
; __device__ __forceinline__ float silu_mul(float a, float b) { return a * b * __builtin_amdgcn_rcpf(1.0f + __builtin_amdgcn_exp2f(-a * LOG2E)); }
; #define PG8_BAR __builtin_amdgcn_s_barrier()
;     __device__ __forceinline__ void operator()(const f32x4 (&acc)[2][2][4][2], const Unit& u, int wr, int wc, int fr, int fq) const {
;     ...
;             for (int m = 0; m < 4; ++m) { const int row = row0 + ai * HALF + m * 16; const float rs = __shfl(ai ? rsl1 : rsl0, m * 16 + fr); bf16_t* rowp = O + (size_t)row * DFF + col0;
;                 const f32x4 a0 = acc[ai][0][m][0] * rs + ba0, a1 = acc[ai][0][m][1] * rs + ba1, b0 = acc[ai][1][m][0] * rs + bb0, b1 = acc[ai][1][m][1] * rs + bb1;
;                 u32x4 w; w.x = cvt_pk_bf16(silu_mul(a0[0], b0[0]), silu_mul(a0[1], b0[1])); w.y = cvt_pk_bf16(silu_mul(a0[2], b0[2]), silu_mul(a0[3], b0[3]));
;                 w.z = cvt_pk_bf16(silu_mul(a1[0], b1[0]), silu_mul(a1[1], b1[1])); w.w = cvt_pk_bf16(silu_mul(a1[2], b1[2]), silu_mul(a1[3], b1[3]));
;                 *(u32x4*)rowp = w; }
; template <class Epi, class Sched, bool ALIGN_EPI = false, bool SP2 = false>
; __device__ __forceinline__ void gemm_phase(LAS unsigned char* lds, const Gemm g, const Sched& S, const Epi& E) {
;     ...
;         if constexpr (!Epi::AFTER_DRAIN) { E(acc, cur, wr, wc, fr, fq); S.done(cur); }
;         if (!has_next) break;
; #pragma unroll
;         for (int a = 0; a < 2; ++a)
; #pragma unroll
;             for (int b = 0; b < 2; ++b)
; #pragma unroll
;                 for (int m = 0; m < 4; ++m)
; #pragma unroll
;                     for (int n = 0; n < 2; ++n) acc[a][b][m][n] = (f32x4){0.f, 0.f, 0.f, 0.f};
;         cur = nxt; cA = nA; cB = nB; ++ui;
;         if constexpr (ALIGN_EPI) { if (wr == 1) PG8_BAR; }
	v_fma_f32 v46, v46, v50, v78
	v_fma_f32 v47, v47, v50, v79
	v_fma_f32 v38, v38, v50, v70
	v_fma_f32 v39, v39, v50, v71
	v_fma_f32 v54, v36, v50, v68
	v_fma_f32 v55, v37, v50, v69
	v_fma_f32 v36, v34, v50, v66
	v_fma_f32 v37, v35, v50, v67
	v_mul_f32_e32 v35, 0xbfb8aa3b, v46
	v_mul_f32_e32 v34, v46, v38
	v_exp_f32_e32 v35, v35
	v_mul_f32_e32 v38, 0xbfb8aa3b, v47
	v_exp_f32_e32 v38, v38
	v_fma_f32 v48, v48, v50, v80
	v_fma_f32 v49, v49, v50, v81
	v_add_f32_e32 v35, 1.0, v35
	v_rcp_f32_e32 v35, v35
	v_add_f32_e32 v38, 1.0, v38
	v_rcp_f32_e32 v38, v38
	v_fma_f32 v40, v40, v50, v72
	v_fma_f32 v41, v41, v50, v73
	v_mul_f32_e32 v34, v34, v35
	v_mul_f32_e32 v35, v47, v39
	v_mul_f32_e32 v35, v35, v38
	v_mul_f32_e32 v38, 0xbfb8aa3b, v48
	v_exp_f32_e32 v38, v38
	v_mul_f32_e32 v39, 0xbfb8aa3b, v49
	v_exp_f32_e32 v39, v39
	v_cvt_pk_bf16_f32 v34, v34, v35
	v_add_f32_e32 v38, 1.0, v38
	v_rcp_f32_e32 v38, v38
	v_add_f32_e32 v39, 1.0, v39
	v_rcp_f32_e32 v39, v39
	v_mul_f32_e32 v35, v48, v40
	v_mul_f32_e32 v35, v35, v38
	v_mul_f32_e32 v38, v49, v41
	v_fma_f32 v42, v42, v50, v74
	v_fma_f32 v43, v43, v50, v75
	v_mul_f32_e32 v38, v38, v39
	v_cvt_pk_bf16_f32 v35, v35, v38
	v_mul_f32_e32 v38, 0xbfb8aa3b, v42
	v_exp_f32_e32 v38, v38
	v_mul_f32_e32 v36, v42, v36
	v_fma_f32 v44, v44, v50, v76
	v_fma_f32 v45, v45, v50, v77
	v_mul_f32_e32 v37, v43, v37
	v_add_f32_e32 v38, 1.0, v38
	v_rcp_f32_e32 v38, v38
	v_mul_f32_e32 v39, 0xbfb8aa3b, v45
	v_exp_f32_e32 v39, v39
	v_lshl_add_u64 v[52:53], v[52:53], 0, v[164:165]
	v_mul_f32_e32 v36, v36, v38
	v_mul_f32_e32 v38, 0xbfb8aa3b, v43
	v_exp_f32_e32 v38, v38
	v_add_f32_e32 v39, 1.0, v39
	v_rcp_f32_e32 v39, v39
	v_add_f32_e32 v38, 1.0, v38
	v_rcp_f32_e32 v38, v38
	s_nop 0
	v_mul_f32_e32 v37, v37, v38
	v_mul_f32_e32 v38, 0xbfb8aa3b, v44
	v_exp_f32_e32 v38, v38
	v_cvt_pk_bf16_f32 v36, v36, v37
	v_mul_f32_e32 v37, v44, v54
	v_add_f32_e32 v38, 1.0, v38
	v_rcp_f32_e32 v38, v38
	s_nop 0
	v_mul_f32_e32 v37, v37, v38
	v_mul_f32_e32 v38, v45, v55
	v_mul_f32_e32 v38, v38, v39
	v_cvt_pk_bf16_f32 v37, v37, v38
	global_store_dwordx4 v[52:53], v[34:37], off
	ds_bpermute_b32 v34, v179, v82 offset:128
	s_nop 0
	v_add_u32_e32 v35, 0xa0, v180
	v_mad_i64_i32 v[36:37], s[2:3], v35, s46, v[162:163]
	s_waitcnt lgkmcnt(0)
	v_fma_f32 v30, v30, v34, v78
	v_fma_f32 v31, v31, v34, v79
	v_fma_f32 v22, v22, v34, v70
	v_fma_f32 v23, v23, v34, v71
	v_fma_f32 v38, v20, v34, v68
	v_fma_f32 v39, v21, v34, v69
	v_fma_f32 v20, v18, v34, v66
	v_fma_f32 v21, v19, v34, v67
	v_mul_f32_e32 v19, 0xbfb8aa3b, v30
	v_mul_f32_e32 v18, v30, v22
	v_exp_f32_e32 v19, v19
	v_mul_f32_e32 v22, 0xbfb8aa3b, v31
	v_exp_f32_e32 v22, v22
	v_fma_f32 v32, v32, v34, v80
	v_fma_f32 v33, v33, v34, v81
	v_add_f32_e32 v19, 1.0, v19
	v_rcp_f32_e32 v19, v19
	v_add_f32_e32 v22, 1.0, v22
	v_rcp_f32_e32 v22, v22
	v_fma_f32 v24, v24, v34, v72
	v_fma_f32 v25, v25, v34, v73
	v_mul_f32_e32 v18, v18, v19
	v_mul_f32_e32 v19, v31, v23
	v_mul_f32_e32 v19, v19, v22
	v_mul_f32_e32 v22, 0xbfb8aa3b, v32
	v_exp_f32_e32 v22, v22
	v_mul_f32_e32 v23, 0xbfb8aa3b, v33
	v_exp_f32_e32 v23, v23
	v_cvt_pk_bf16_f32 v18, v18, v19
	v_add_f32_e32 v22, 1.0, v22
	v_rcp_f32_e32 v22, v22
	v_add_f32_e32 v23, 1.0, v23
	v_rcp_f32_e32 v23, v23
	v_mul_f32_e32 v19, v32, v24
	v_mul_f32_e32 v19, v19, v22
	v_mul_f32_e32 v22, v33, v25
	v_fma_f32 v26, v26, v34, v74
	v_fma_f32 v27, v27, v34, v75
	v_mul_f32_e32 v22, v22, v23
	v_cvt_pk_bf16_f32 v19, v19, v22
	v_mul_f32_e32 v22, 0xbfb8aa3b, v26
	v_exp_f32_e32 v22, v22
	v_mul_f32_e32 v20, v26, v20
	v_fma_f32 v28, v28, v34, v76
	v_fma_f32 v29, v29, v34, v77
	v_mul_f32_e32 v21, v27, v21
	v_add_f32_e32 v22, 1.0, v22
	v_rcp_f32_e32 v22, v22
	v_mul_f32_e32 v23, 0xbfb8aa3b, v29
	v_exp_f32_e32 v23, v23
	v_lshl_add_u64 v[36:37], v[36:37], 0, v[164:165]
	v_mul_f32_e32 v20, v20, v22
	v_mul_f32_e32 v22, 0xbfb8aa3b, v27
	v_exp_f32_e32 v22, v22
	v_add_f32_e32 v23, 1.0, v23
	v_rcp_f32_e32 v23, v23
	v_add_f32_e32 v22, 1.0, v22
	v_rcp_f32_e32 v22, v22
	s_nop 0
	v_mul_f32_e32 v21, v21, v22
	v_mul_f32_e32 v22, 0xbfb8aa3b, v28
	v_exp_f32_e32 v22, v22
	v_cvt_pk_bf16_f32 v20, v20, v21
	v_mul_f32_e32 v21, v28, v38
	v_add_f32_e32 v22, 1.0, v22
	v_rcp_f32_e32 v22, v22
	s_nop 0
	v_mul_f32_e32 v21, v21, v22
	v_mul_f32_e32 v22, v29, v39
	v_mul_f32_e32 v22, v22, v23
	v_cvt_pk_bf16_f32 v21, v21, v22
	global_store_dwordx4 v[36:37], v[18:21], off
	ds_bpermute_b32 v18, v179, v82 offset:192
	s_nop 0
	v_add_u32_e32 v19, 0xb0, v180
	v_mad_i64_i32 v[20:21], s[2:3], v19, s46, v[162:163]
	s_waitcnt lgkmcnt(0)
	v_fma_f32 v14, v14, v18, v78
	v_fma_f32 v15, v15, v18, v79
	v_fma_f32 v6, v6, v18, v70
	v_fma_f32 v7, v7, v18, v71
	v_fma_f32 v22, v4, v18, v68
	v_fma_f32 v23, v5, v18, v69
	v_fma_f32 v4, v2, v18, v66
	v_fma_f32 v5, v3, v18, v67
	v_mul_f32_e32 v3, 0xbfb8aa3b, v14
	v_mul_f32_e32 v2, v14, v6
	v_exp_f32_e32 v3, v3
	v_mul_f32_e32 v6, 0xbfb8aa3b, v15
	v_exp_f32_e32 v6, v6
	v_fma_f32 v16, v16, v18, v80
	v_fma_f32 v17, v17, v18, v81
	v_add_f32_e32 v3, 1.0, v3
	v_rcp_f32_e32 v3, v3
	v_add_f32_e32 v6, 1.0, v6
	v_rcp_f32_e32 v6, v6
	v_fma_f32 v8, v8, v18, v72
	v_fma_f32 v9, v9, v18, v73
	v_mul_f32_e32 v2, v2, v3
	v_mul_f32_e32 v3, v15, v7
	v_mul_f32_e32 v3, v3, v6
	v_mul_f32_e32 v6, 0xbfb8aa3b, v16
	v_exp_f32_e32 v6, v6
	v_mul_f32_e32 v7, 0xbfb8aa3b, v17
	v_exp_f32_e32 v7, v7
	v_cvt_pk_bf16_f32 v2, v2, v3
	v_add_f32_e32 v6, 1.0, v6
	v_rcp_f32_e32 v6, v6
	v_add_f32_e32 v7, 1.0, v7
	v_rcp_f32_e32 v7, v7
	v_mul_f32_e32 v3, v16, v8
	v_mul_f32_e32 v3, v3, v6
	v_mul_f32_e32 v6, v17, v9
	v_fma_f32 v10, v10, v18, v74
	v_fma_f32 v11, v11, v18, v75
	v_mul_f32_e32 v6, v6, v7
	v_cvt_pk_bf16_f32 v3, v3, v6
	v_mul_f32_e32 v6, 0xbfb8aa3b, v10
	v_exp_f32_e32 v6, v6
	v_mul_f32_e32 v4, v10, v4
	v_fma_f32 v12, v12, v18, v76
	v_fma_f32 v13, v13, v18, v77
	v_mul_f32_e32 v5, v11, v5
	v_add_f32_e32 v6, 1.0, v6
	v_rcp_f32_e32 v6, v6
	v_mul_f32_e32 v7, 0xbfb8aa3b, v13
	v_exp_f32_e32 v7, v7
	v_lshl_add_u64 v[20:21], v[20:21], 0, v[164:165]
	v_mul_f32_e32 v4, v4, v6
	v_mul_f32_e32 v6, 0xbfb8aa3b, v11
	v_exp_f32_e32 v6, v6
	v_add_f32_e32 v7, 1.0, v7
	v_rcp_f32_e32 v7, v7
	s_mov_b64 s[2:3], -1
	v_add_f32_e32 v6, 1.0, v6
	v_rcp_f32_e32 v6, v6
	s_nop 0
	v_mul_f32_e32 v5, v5, v6
	v_mul_f32_e32 v6, 0xbfb8aa3b, v12
	v_exp_f32_e32 v6, v6
	v_cvt_pk_bf16_f32 v4, v4, v5
	v_mul_f32_e32 v5, v12, v22
	v_add_f32_e32 v6, 1.0, v6
	v_rcp_f32_e32 v6, v6
	s_nop 0
	v_mul_f32_e32 v5, v5, v6
	v_mul_f32_e32 v6, v13, v23
	v_mul_f32_e32 v6, v6, v7
	v_cvt_pk_bf16_f32 v5, v5, v6
	global_store_dwordx4 v[20:21], v[2:5], off
	s_cbranch_vccz .LBB0_1818
	s_andn2_b64 vcc, exec, s[4:5]
	s_cbranch_vccnz .LBB0_1817
	s_barrier
	s_branch .LBB0_1817

; __device__ __forceinline__ unsigned cvt_pk_bf16(float lo, float hi) { unsigned r; asm volatile("v_cvt_pk_bf16_f32 %0, %1, %2" : "=v"(r) : "v"(lo), "v"(hi)); return r; }
; __device__ __forceinline__ float silu_mul(float a, float b) { return a * b * __builtin_amdgcn_rcpf(1.0f + __builtin_amdgcn_exp2f(-a * LOG2E)); }
; __device__ __forceinline__ float row_rstd(const float* ss, int row) { return 1.0f / sqrtf(ss[row] * (1.0f / DM) + 1e-6f); }
;     __device__ __forceinline__ void operator()(const f32x4 (&acc)[2][2][4][2], const Unit& u, int wr, int wc, int fr, int fq) const {
;         const int row0 = u.pm * BM + wr * 64 + fr, col0 = u.pn * HALF + wc * 32 + 8 * fq;
;         const int s = (u.pm < ML / BM) ? (u.pm >> 5) : 4;
;         const float* bp = bias + (size_t)s * BIAS_N + u.pn * BM + wc * 32 + 8 * fq;
;         const f32x4 ba0 = *(const f32x4*)bp, ba1 = *(const f32x4*)(bp + 4), bb0 = *(const f32x4*)(bp + HALF), bb1 = *(const f32x4*)(bp + HALF + 4);
;         const int lane = fq * 16 + fr;
;         const float rsl0 = row_rstd(ss, u.pm * BM + wr * 64 + lane), rsl1 = row_rstd(ss, u.pm * BM + HALF + wr * 64 + lane);
; #pragma unroll
;         for (int ai = 0; ai < 2; ++ai)
; #pragma unroll
;             for (int m = 0; m < 4; ++m) { const int row = row0 + ai * HALF + m * 16; const float rs = __shfl(ai ? rsl1 : rsl0, m * 16 + fr); bf16_t* rowp = O + (size_t)row * DFF + col0;
;                 const f32x4 a0 = acc[ai][0][m][0] * rs + ba0, a1 = acc[ai][0][m][1] * rs + ba1, b0 = acc[ai][1][m][0] * rs + bb0, b1 = acc[ai][1][m][1] * rs + bb1;
;                 u32x4 w; w.x = cvt_pk_bf16(silu_mul(a0[0], b0[0]), silu_mul(a0[1], b0[1])); w.y = cvt_pk_bf16(silu_mul(a0[2], b0[2]), silu_mul(a0[3], b0[3]));
;                 w.z = cvt_pk_bf16(silu_mul(a1[0], b1[0]), silu_mul(a1[1], b1[1])); w.w = cvt_pk_bf16(silu_mul(a1[2], b1[2]), silu_mul(a1[3], b1[3]));
;                 *(u32x4*)rowp = w; }
.LBB0_2921:
	s_lshl_b32 s2, s2, 8
	s_add_i32 s11, s2, s34
	s_lshl_b64 s[18:19], s[18:19], 2
	s_add_u32 s13, s35, s18
	s_addc_u32 s18, s38, s19
	s_lshl_b32 s2, s3, 8
	v_lshl_or_b32 v164, s3, 7, v172
	s_ashr_i32 s3, s2, 31
	s_lshl_b64 s[2:3], s[2:3], 2
	s_add_u32 s2, s13, s2
	s_addc_u32 s3, s18, s3
	v_or_b32_e32 v162, s11, v170
	s_add_u32 s2, s2, s44
	v_ashrrev_i32_e32 v163, 31, v162
	s_addc_u32 s3, s3, 0
	v_lshl_add_u64 v[162:163], v[162:163], 2, s[0:1]
	v_mov_b32_e32 v74, v234
	v_mov_b32_e32 v75, v235
	v_mov_b32_e32 v76, v236
	v_mov_b32_e32 v77, v237
	v_mov_b32_e32 v78, v238
	v_mov_b32_e32 v79, v239
	v_mov_b32_e32 v80, v240
	v_mov_b32_e32 v81, v241
	v_mov_b32_e32 v66, v242
	v_mov_b32_e32 v67, v243
	v_mov_b32_e32 v68, v244
	v_mov_b32_e32 v69, v245
	v_mov_b32_e32 v70, v246
	v_mov_b32_e32 v71, v247
	v_mov_b32_e32 v72, v248
	v_mov_b32_e32 v73, v249
	v_or_b32_e32 v180, s11, v1
	v_mov_b32_e32 v162, v250
	s_waitcnt vmcnt(0)
	v_fmamk_f32 v162, v162, 0x3a000000, v177
	v_cmp_gt_f32_e32 vcc, s45, v162
	v_mul_f32_e32 v163, 0x4f800000, v162
	s_nop 0
	v_cndmask_b32_e32 v162, v162, v163, vcc
	v_sqrt_f32_e32 v163, v162
	s_nop 0
	v_add_u32_e32 v165, -1, v163
	v_fma_f32 v166, -v165, v163, v162
	v_cmp_ge_f32_e64 s[2:3], 0, v166
	v_add_u32_e32 v166, 1, v163
	s_nop 0
	v_cndmask_b32_e64 v165, v163, v165, s[2:3]
	v_fma_f32 v163, -v166, v163, v162
	v_cmp_lt_f32_e64 s[2:3], 0, v163
	s_nop 1
	v_cndmask_b32_e64 v163, v165, v166, s[2:3]
	v_mul_f32_e32 v165, 0x37800000, v163
	v_cndmask_b32_e32 v163, v163, v165, vcc
	v_cmp_class_f32_e32 vcc, v162, v178
	s_nop 1
	v_cndmask_b32_e32 v166, v163, v162, vcc
	v_add_u32_e32 v162, s11, v171
	v_ashrrev_i32_e32 v163, 31, v162
	v_lshl_add_u64 v[162:163], v[162:163], 2, s[0:1]
	v_mov_b32_e32 v162, v251
	v_fmamk_f32 v162, v162, 0x3a000000, v177
	v_cmp_gt_f32_e32 vcc, s45, v162
	v_mul_f32_e32 v163, 0x4f800000, v162
	s_nop 0
	v_cndmask_b32_e32 v162, v162, v163, vcc
	v_sqrt_f32_e32 v163, v162
	s_nop 0
	v_add_u32_e32 v165, -1, v163
	v_fma_f32 v167, -v165, v163, v162
	v_cmp_ge_f32_e64 s[2:3], 0, v167
	v_add_u32_e32 v167, 1, v163
	s_nop 0
	v_cndmask_b32_e64 v165, v163, v165, s[2:3]
	v_fma_f32 v163, -v167, v163, v162
	v_cmp_lt_f32_e64 s[2:3], 0, v163
	s_nop 1
	v_cndmask_b32_e64 v163, v165, v167, s[2:3]
	v_mul_f32_e32 v165, 0x37800000, v163
	v_cndmask_b32_e32 v163, v163, v165, vcc
	v_cmp_class_f32_e32 vcc, v162, v178
	v_ashrrev_i32_e32 v165, 31, v164
	v_lshlrev_b64 v[164:165], 1, v[164:165]
	v_cndmask_b32_e32 v181, v163, v162, vcc
	v_div_scale_f32 v162, s[2:3], v166, v166, 1.0
	v_rcp_f32_e32 v163, v162
	s_nop 0
	v_fma_f32 v167, -v162, v163, 1.0
	v_fmac_f32_e32 v163, v167, v163
	v_div_scale_f32 v167, vcc, 1.0, v166, 1.0
	v_mul_f32_e32 v168, v167, v163
	v_fma_f32 v182, -v162, v168, v167
	v_fmac_f32_e32 v168, v182, v163
	v_fma_f32 v162, -v162, v168, v167
	v_div_fmas_f32 v162, v162, v163, v168
	v_div_fixup_f32 v182, v162, v166, 1.0
	ds_bpermute_b32 v168, v179, v182
	v_mov_b64_e32 v[162:163], s[96:97]
	v_mad_i64_i32 v[166:167], s[2:3], v180, s43, v[162:163]
	v_lshl_add_u64 v[166:167], v[166:167], 0, v[164:165]
	s_waitcnt lgkmcnt(0)
	v_fma_f32 v142, v142, v168, v78
	v_fma_f32 v143, v143, v168, v79
	v_fma_f32 v134, v134, v168, v70
	v_fma_f32 v135, v135, v168, v71
	v_fma_f32 v184, v132, v168, v68
	v_fma_f32 v185, v133, v168, v69
	v_fma_f32 v132, v130, v168, v66
	v_fma_f32 v133, v131, v168, v67
	v_mul_f32_e32 v131, 0xbfb8aa3b, v142
	v_mul_f32_e32 v130, v142, v134
	v_exp_f32_e32 v131, v131
	v_mul_f32_e32 v134, 0xbfb8aa3b, v143
	v_exp_f32_e32 v134, v134
	v_fma_f32 v144, v144, v168, v80
	v_fma_f32 v145, v145, v168, v81
	v_add_f32_e32 v131, 1.0, v131
	v_rcp_f32_e32 v131, v131
	v_add_f32_e32 v134, 1.0, v134
	v_rcp_f32_e32 v134, v134
	v_fma_f32 v136, v136, v168, v72
	v_fma_f32 v137, v137, v168, v73
	v_mul_f32_e32 v130, v130, v131
	v_mul_f32_e32 v131, v143, v135
	v_mul_f32_e32 v131, v131, v134
	v_mul_f32_e32 v134, 0xbfb8aa3b, v144
	v_exp_f32_e32 v134, v134
	v_mul_f32_e32 v135, 0xbfb8aa3b, v145
	v_exp_f32_e32 v135, v135
	v_cvt_pk_bf16_f32 v130, v130, v131
	v_add_f32_e32 v134, 1.0, v134
	v_rcp_f32_e32 v134, v134
	v_add_f32_e32 v135, 1.0, v135
	v_rcp_f32_e32 v135, v135
	v_mul_f32_e32 v131, v144, v136
	v_mul_f32_e32 v131, v131, v134
	v_mul_f32_e32 v134, v145, v137
	v_fma_f32 v138, v138, v168, v74
	v_fma_f32 v139, v139, v168, v75
	v_mul_f32_e32 v134, v134, v135
	v_cvt_pk_bf16_f32 v131, v131, v134
	v_mul_f32_e32 v134, 0xbfb8aa3b, v138
	v_exp_f32_e32 v134, v134
	v_mul_f32_e32 v132, v138, v132
	v_fma_f32 v140, v140, v168, v76
	v_fma_f32 v141, v141, v168, v77
	v_mul_f32_e32 v133, v139, v133
	v_add_f32_e32 v134, 1.0, v134
	v_rcp_f32_e32 v134, v134
	v_mul_f32_e32 v135, 0xbfb8aa3b, v141
	v_exp_f32_e32 v135, v135
	v_mul_f32_e32 v132, v132, v134
	v_mul_f32_e32 v134, 0xbfb8aa3b, v139
	v_exp_f32_e32 v134, v134
	v_add_f32_e32 v135, 1.0, v135
	v_rcp_f32_e32 v135, v135
	v_add_f32_e32 v134, 1.0, v134
	v_rcp_f32_e32 v134, v134
	s_nop 0
	v_mul_f32_e32 v133, v133, v134
	v_mul_f32_e32 v134, 0xbfb8aa3b, v140
	v_exp_f32_e32 v134, v134
	v_cvt_pk_bf16_f32 v132, v132, v133
	v_mul_f32_e32 v133, v140, v184
	v_add_f32_e32 v134, 1.0, v134
	v_rcp_f32_e32 v134, v134
	s_nop 0
	v_mul_f32_e32 v133, v133, v134
	v_mul_f32_e32 v134, v141, v185
	v_mul_f32_e32 v134, v134, v135
	v_cvt_pk_bf16_f32 v133, v133, v134
	global_store_dwordx4 v[166:167], v[130:133], off
	ds_bpermute_b32 v130, v179, v182 offset:64
	s_nop 0
	v_or_b32_e32 v131, 16, v180
	v_mad_i64_i32 v[132:133], s[2:3], v131, s43, v[162:163]
	s_waitcnt lgkmcnt(0)
; __device__ __forceinline__ unsigned cvt_pk_bf16(float lo, float hi) { unsigned r; asm volatile("v_cvt_pk_bf16_f32 %0, %1, %2" : "=v"(r) : "v"(lo), "v"(hi)); return r; }
; __device__ __forceinline__ float silu_mul(float a, float b) { return a * b * __builtin_amdgcn_rcpf(1.0f + __builtin_amdgcn_exp2f(-a * LOG2E)); }
;     __device__ __forceinline__ void operator()(const f32x4 (&acc)[2][2][4][2], const Unit& u, int wr, int wc, int fr, int fq) const {
;     ...
;             for (int m = 0; m < 4; ++m) { const int row = row0 + ai * HALF + m * 16; const float rs = __shfl(ai ? rsl1 : rsl0, m * 16 + fr); bf16_t* rowp = O + (size_t)row * DFF + col0;
;                 const f32x4 a0 = acc[ai][0][m][0] * rs + ba0, a1 = acc[ai][0][m][1] * rs + ba1, b0 = acc[ai][1][m][0] * rs + bb0, b1 = acc[ai][1][m][1] * rs + bb1;
;                 u32x4 w; w.x = cvt_pk_bf16(silu_mul(a0[0], b0[0]), silu_mul(a0[1], b0[1])); w.y = cvt_pk_bf16(silu_mul(a0[2], b0[2]), silu_mul(a0[3], b0[3]));
;                 w.z = cvt_pk_bf16(silu_mul(a1[0], b1[0]), silu_mul(a1[1], b1[1])); w.w = cvt_pk_bf16(silu_mul(a1[2], b1[2]), silu_mul(a1[3], b1[3]));
;                 *(u32x4*)rowp = w; }
	v_fma_f32 v126, v126, v130, v78
	v_fma_f32 v127, v127, v130, v79
	v_fma_f32 v118, v118, v130, v70
	v_fma_f32 v119, v119, v130, v71
	v_fma_f32 v134, v116, v130, v68
	v_fma_f32 v135, v117, v130, v69
	v_fma_f32 v116, v114, v130, v66
	v_fma_f32 v117, v115, v130, v67
	v_mul_f32_e32 v115, 0xbfb8aa3b, v126
	v_mul_f32_e32 v114, v126, v118
	v_exp_f32_e32 v115, v115
	v_mul_f32_e32 v118, 0xbfb8aa3b, v127
	v_exp_f32_e32 v118, v118
	v_fma_f32 v128, v128, v130, v80
	v_fma_f32 v129, v129, v130, v81
	v_add_f32_e32 v115, 1.0, v115
	v_rcp_f32_e32 v115, v115
	v_add_f32_e32 v118, 1.0, v118
	v_rcp_f32_e32 v118, v118
	v_fma_f32 v120, v120, v130, v72
	v_fma_f32 v121, v121, v130, v73
	v_mul_f32_e32 v114, v114, v115
	v_mul_f32_e32 v115, v127, v119
	v_mul_f32_e32 v115, v115, v118
	v_mul_f32_e32 v118, 0xbfb8aa3b, v128
	v_exp_f32_e32 v118, v118
	v_mul_f32_e32 v119, 0xbfb8aa3b, v129
	v_exp_f32_e32 v119, v119
	v_cvt_pk_bf16_f32 v114, v114, v115
	v_add_f32_e32 v118, 1.0, v118
	v_rcp_f32_e32 v118, v118
	v_add_f32_e32 v119, 1.0, v119
	v_rcp_f32_e32 v119, v119
	v_mul_f32_e32 v115, v128, v120
	v_mul_f32_e32 v115, v115, v118
	v_mul_f32_e32 v118, v129, v121
	v_fma_f32 v122, v122, v130, v74
	v_fma_f32 v123, v123, v130, v75
	v_mul_f32_e32 v118, v118, v119
	v_cvt_pk_bf16_f32 v115, v115, v118
	v_mul_f32_e32 v118, 0xbfb8aa3b, v122
	v_exp_f32_e32 v118, v118
	v_mul_f32_e32 v116, v122, v116
	v_fma_f32 v124, v124, v130, v76
	v_fma_f32 v125, v125, v130, v77
	v_mul_f32_e32 v117, v123, v117
	v_add_f32_e32 v118, 1.0, v118
	v_rcp_f32_e32 v118, v118
	v_mul_f32_e32 v119, 0xbfb8aa3b, v125
	v_exp_f32_e32 v119, v119
	v_lshl_add_u64 v[132:133], v[132:133], 0, v[164:165]
	v_mul_f32_e32 v116, v116, v118
	v_mul_f32_e32 v118, 0xbfb8aa3b, v123
	v_exp_f32_e32 v118, v118
	v_add_f32_e32 v119, 1.0, v119
	v_rcp_f32_e32 v119, v119
	v_add_f32_e32 v118, 1.0, v118
	v_rcp_f32_e32 v118, v118
	s_nop 0
	v_mul_f32_e32 v117, v117, v118
	v_mul_f32_e32 v118, 0xbfb8aa3b, v124
	v_exp_f32_e32 v118, v118
	v_cvt_pk_bf16_f32 v116, v116, v117
	v_mul_f32_e32 v117, v124, v134
	v_add_f32_e32 v118, 1.0, v118
	v_rcp_f32_e32 v118, v118
	s_nop 0
	v_mul_f32_e32 v117, v117, v118
	v_mul_f32_e32 v118, v125, v135
	v_mul_f32_e32 v118, v118, v119
	v_cvt_pk_bf16_f32 v117, v117, v118
	global_store_dwordx4 v[132:133], v[114:117], off
	ds_bpermute_b32 v114, v179, v182 offset:128
	s_nop 0
	v_or_b32_e32 v115, 32, v180
	v_mad_i64_i32 v[116:117], s[2:3], v115, s43, v[162:163]
	s_waitcnt lgkmcnt(0)
	v_fma_f32 v110, v110, v114, v78
	v_fma_f32 v111, v111, v114, v79
	v_fma_f32 v102, v102, v114, v70
	v_fma_f32 v103, v103, v114, v71
	v_fma_f32 v118, v100, v114, v68
	v_fma_f32 v119, v101, v114, v69
	v_fma_f32 v100, v98, v114, v66
	v_fma_f32 v101, v99, v114, v67
	v_mul_f32_e32 v99, 0xbfb8aa3b, v110
	v_mul_f32_e32 v98, v110, v102
	v_exp_f32_e32 v99, v99
	v_mul_f32_e32 v102, 0xbfb8aa3b, v111
	v_exp_f32_e32 v102, v102
	v_fma_f32 v112, v112, v114, v80
	v_fma_f32 v113, v113, v114, v81
	v_add_f32_e32 v99, 1.0, v99
	v_rcp_f32_e32 v99, v99
	v_add_f32_e32 v102, 1.0, v102
	v_rcp_f32_e32 v102, v102
	v_fma_f32 v104, v104, v114, v72
	v_fma_f32 v105, v105, v114, v73
	v_mul_f32_e32 v98, v98, v99
	v_mul_f32_e32 v99, v111, v103
	v_mul_f32_e32 v99, v99, v102
	v_mul_f32_e32 v102, 0xbfb8aa3b, v112
	v_exp_f32_e32 v102, v102
	v_mul_f32_e32 v103, 0xbfb8aa3b, v113
	v_exp_f32_e32 v103, v103
	v_cvt_pk_bf16_f32 v98, v98, v99
	v_add_f32_e32 v102, 1.0, v102
	v_rcp_f32_e32 v102, v102
	v_add_f32_e32 v103, 1.0, v103
	v_rcp_f32_e32 v103, v103
	v_mul_f32_e32 v99, v112, v104
	v_mul_f32_e32 v99, v99, v102
	v_mul_f32_e32 v102, v113, v105
	v_fma_f32 v106, v106, v114, v74
	v_fma_f32 v107, v107, v114, v75
	v_mul_f32_e32 v102, v102, v103
	v_cvt_pk_bf16_f32 v99, v99, v102
	v_mul_f32_e32 v102, 0xbfb8aa3b, v106
	v_exp_f32_e32 v102, v102
	v_mul_f32_e32 v100, v106, v100
	v_fma_f32 v108, v108, v114, v76
	v_fma_f32 v109, v109, v114, v77
	v_mul_f32_e32 v101, v107, v101
	v_add_f32_e32 v102, 1.0, v102
	v_rcp_f32_e32 v102, v102
	v_mul_f32_e32 v103, 0xbfb8aa3b, v109
	v_exp_f32_e32 v103, v103
	v_lshl_add_u64 v[116:117], v[116:117], 0, v[164:165]
	v_mul_f32_e32 v100, v100, v102
	v_mul_f32_e32 v102, 0xbfb8aa3b, v107
	v_exp_f32_e32 v102, v102
	v_add_f32_e32 v103, 1.0, v103
	v_rcp_f32_e32 v103, v103
	v_add_f32_e32 v102, 1.0, v102
	v_rcp_f32_e32 v102, v102
	s_nop 0
	v_mul_f32_e32 v101, v101, v102
	v_mul_f32_e32 v102, 0xbfb8aa3b, v108
	v_exp_f32_e32 v102, v102
	v_cvt_pk_bf16_f32 v100, v100, v101
	v_mul_f32_e32 v101, v108, v118
	v_add_f32_e32 v102, 1.0, v102
	v_rcp_f32_e32 v102, v102
	s_nop 0
	v_mul_f32_e32 v101, v101, v102
	v_mul_f32_e32 v102, v109, v119
	v_mul_f32_e32 v102, v102, v103
	v_cvt_pk_bf16_f32 v101, v101, v102
	global_store_dwordx4 v[116:117], v[98:101], off
	ds_bpermute_b32 v98, v179, v182 offset:192
	s_nop 0
	v_or_b32_e32 v99, 48, v180
	v_mad_i64_i32 v[100:101], s[2:3], v99, s43, v[162:163]
	s_waitcnt lgkmcnt(0)
; __device__ __forceinline__ unsigned cvt_pk_bf16(float lo, float hi) { unsigned r; asm volatile("v_cvt_pk_bf16_f32 %0, %1, %2" : "=v"(r) : "v"(lo), "v"(hi)); return r; }
; __device__ __forceinline__ float silu_mul(float a, float b) { return a * b * __builtin_amdgcn_rcpf(1.0f + __builtin_amdgcn_exp2f(-a * LOG2E)); }
; __device__ __forceinline__ float row_rstd(const float* ss, int row) { return 1.0f / sqrtf(ss[row] * (1.0f / DM) + 1e-6f); }
;     __device__ __forceinline__ void operator()(const f32x4 (&acc)[2][2][4][2], const Unit& u, int wr, int wc, int fr, int fq) const {
;     ...
;             for (int m = 0; m < 4; ++m) { const int row = row0 + ai * HALF + m * 16; const float rs = __shfl(ai ? rsl1 : rsl0, m * 16 + fr); bf16_t* rowp = O + (size_t)row * DFF + col0;
;                 const f32x4 a0 = acc[ai][0][m][0] * rs + ba0, a1 = acc[ai][0][m][1] * rs + ba1, b0 = acc[ai][1][m][0] * rs + bb0, b1 = acc[ai][1][m][1] * rs + bb1;
;                 u32x4 w; w.x = cvt_pk_bf16(silu_mul(a0[0], b0[0]), silu_mul(a0[1], b0[1])); w.y = cvt_pk_bf16(silu_mul(a0[2], b0[2]), silu_mul(a0[3], b0[3]));
;                 w.z = cvt_pk_bf16(silu_mul(a1[0], b1[0]), silu_mul(a1[1], b1[1])); w.w = cvt_pk_bf16(silu_mul(a1[2], b1[2]), silu_mul(a1[3], b1[3]));
;                 *(u32x4*)rowp = w; }
	v_fma_f32 v94, v94, v98, v78
	v_fma_f32 v95, v95, v98, v79
	v_fma_f32 v86, v86, v98, v70
	v_fma_f32 v87, v87, v98, v71
	v_fma_f32 v102, v84, v98, v68
	v_fma_f32 v103, v85, v98, v69
	v_fma_f32 v84, v82, v98, v66
	v_fma_f32 v85, v83, v98, v67
	v_mul_f32_e32 v83, 0xbfb8aa3b, v94
	v_mul_f32_e32 v82, v94, v86
	v_exp_f32_e32 v83, v83
	v_mul_f32_e32 v86, 0xbfb8aa3b, v95
	v_exp_f32_e32 v86, v86
	v_fma_f32 v96, v96, v98, v80
	v_fma_f32 v97, v97, v98, v81
	v_add_f32_e32 v83, 1.0, v83
	v_rcp_f32_e32 v83, v83
	v_add_f32_e32 v86, 1.0, v86
	v_rcp_f32_e32 v86, v86
	v_fma_f32 v88, v88, v98, v72
	v_fma_f32 v89, v89, v98, v73
	v_mul_f32_e32 v82, v82, v83
	v_mul_f32_e32 v83, v95, v87
	v_mul_f32_e32 v83, v83, v86
	v_mul_f32_e32 v86, 0xbfb8aa3b, v96
	v_exp_f32_e32 v86, v86
	v_mul_f32_e32 v87, 0xbfb8aa3b, v97
	v_exp_f32_e32 v87, v87
	v_cvt_pk_bf16_f32 v82, v82, v83
	v_add_f32_e32 v86, 1.0, v86
	v_rcp_f32_e32 v86, v86
	v_add_f32_e32 v87, 1.0, v87
	v_rcp_f32_e32 v87, v87
	v_mul_f32_e32 v83, v96, v88
	v_mul_f32_e32 v83, v83, v86
	v_mul_f32_e32 v86, v97, v89
	v_fma_f32 v90, v90, v98, v74
	v_fma_f32 v91, v91, v98, v75
	v_mul_f32_e32 v86, v86, v87
	v_cvt_pk_bf16_f32 v83, v83, v86
	v_mul_f32_e32 v86, 0xbfb8aa3b, v90
	v_exp_f32_e32 v86, v86
	v_mul_f32_e32 v84, v90, v84
	v_fma_f32 v92, v92, v98, v76
	v_fma_f32 v93, v93, v98, v77
	v_mul_f32_e32 v85, v91, v85
	v_add_f32_e32 v86, 1.0, v86
	v_rcp_f32_e32 v86, v86
	v_mul_f32_e32 v87, 0xbfb8aa3b, v93
	v_exp_f32_e32 v87, v87
	v_lshl_add_u64 v[100:101], v[100:101], 0, v[164:165]
	v_mul_f32_e32 v84, v84, v86
	v_mul_f32_e32 v86, 0xbfb8aa3b, v91
	v_exp_f32_e32 v86, v86
	v_add_f32_e32 v87, 1.0, v87
	v_rcp_f32_e32 v87, v87
	v_add_f32_e32 v86, 1.0, v86
	v_rcp_f32_e32 v86, v86
	s_nop 0
	v_mul_f32_e32 v85, v85, v86
	v_mul_f32_e32 v86, 0xbfb8aa3b, v92
	v_exp_f32_e32 v86, v86
	v_cvt_pk_bf16_f32 v84, v84, v85
	v_mul_f32_e32 v85, v92, v102
	v_add_f32_e32 v86, 1.0, v86
	v_rcp_f32_e32 v86, v86
	s_nop 0
	v_mul_f32_e32 v85, v85, v86
	v_mul_f32_e32 v86, v93, v103
	v_mul_f32_e32 v86, v86, v87
	v_cvt_pk_bf16_f32 v85, v85, v86
	global_store_dwordx4 v[100:101], v[82:85], off
	s_nop 1
	v_div_scale_f32 v82, s[2:3], v181, v181, 1.0
	v_rcp_f32_e32 v84, v82
	v_add_u32_e32 v83, 0x80, v180
	v_fma_f32 v85, -v82, v84, 1.0
	v_fmac_f32_e32 v84, v85, v84
	v_div_scale_f32 v85, vcc, 1.0, v181, 1.0
	v_mul_f32_e32 v86, v85, v84
	v_fma_f32 v87, -v82, v86, v85
	v_fmac_f32_e32 v86, v87, v84
	v_fma_f32 v82, -v82, v86, v85
	v_div_fmas_f32 v82, v82, v84, v86
	v_div_fixup_f32 v82, v82, v181, 1.0
	ds_bpermute_b32 v84, v179, v82
	v_mad_i64_i32 v[86:87], s[2:3], v83, s43, v[162:163]
	v_lshl_add_u64 v[86:87], v[86:87], 0, v[164:165]
	s_and_b64 vcc, s[36:37], exec
	s_waitcnt lgkmcnt(0)
	v_fma_f32 v62, v62, v84, v78
	v_fma_f32 v63, v63, v84, v79
	v_fma_f32 v54, v54, v84, v70
	v_fma_f32 v55, v55, v84, v71
	v_fma_f32 v88, v52, v84, v68
	v_fma_f32 v89, v53, v84, v69
	v_fma_f32 v52, v50, v84, v66
	v_fma_f32 v53, v51, v84, v67
	v_mul_f32_e32 v51, 0xbfb8aa3b, v62
	v_mul_f32_e32 v50, v62, v54
	v_exp_f32_e32 v51, v51
	v_mul_f32_e32 v54, 0xbfb8aa3b, v63
	v_exp_f32_e32 v54, v54
	v_fma_f32 v64, v64, v84, v80
	v_fma_f32 v65, v65, v84, v81
	v_add_f32_e32 v51, 1.0, v51
	v_rcp_f32_e32 v51, v51
	v_add_f32_e32 v54, 1.0, v54
	v_rcp_f32_e32 v54, v54
	v_fma_f32 v56, v56, v84, v72
	v_fma_f32 v57, v57, v84, v73
	v_mul_f32_e32 v50, v50, v51
	v_mul_f32_e32 v51, v63, v55
	v_mul_f32_e32 v51, v51, v54
	v_mul_f32_e32 v54, 0xbfb8aa3b, v64
	v_exp_f32_e32 v54, v54
	v_mul_f32_e32 v55, 0xbfb8aa3b, v65
	v_exp_f32_e32 v55, v55
	v_cvt_pk_bf16_f32 v50, v50, v51
	v_add_f32_e32 v54, 1.0, v54
	v_rcp_f32_e32 v54, v54
	v_add_f32_e32 v55, 1.0, v55
	v_rcp_f32_e32 v55, v55
	v_mul_f32_e32 v51, v64, v56
	v_mul_f32_e32 v51, v51, v54
	v_mul_f32_e32 v54, v65, v57
	v_fma_f32 v58, v58, v84, v74
	v_fma_f32 v59, v59, v84, v75
	v_mul_f32_e32 v54, v54, v55
	v_cvt_pk_bf16_f32 v51, v51, v54
	v_mul_f32_e32 v54, 0xbfb8aa3b, v58
	v_exp_f32_e32 v54, v54
	v_mul_f32_e32 v52, v58, v52
	v_fma_f32 v60, v60, v84, v76
	v_fma_f32 v61, v61, v84, v77
	v_mul_f32_e32 v53, v59, v53
	v_add_f32_e32 v54, 1.0, v54
	v_rcp_f32_e32 v54, v54
	v_mul_f32_e32 v55, 0xbfb8aa3b, v61
	v_exp_f32_e32 v55, v55
	v_mul_f32_e32 v52, v52, v54
	v_mul_f32_e32 v54, 0xbfb8aa3b, v59
	v_exp_f32_e32 v54, v54
	v_add_f32_e32 v55, 1.0, v55
	v_rcp_f32_e32 v55, v55
	v_add_f32_e32 v54, 1.0, v54
	v_rcp_f32_e32 v54, v54
	s_nop 0
	v_mul_f32_e32 v53, v53, v54
	v_mul_f32_e32 v54, 0xbfb8aa3b, v60
	v_exp_f32_e32 v54, v54
	v_cvt_pk_bf16_f32 v52, v52, v53
	v_mul_f32_e32 v53, v60, v88
	v_add_f32_e32 v54, 1.0, v54
	v_rcp_f32_e32 v54, v54
	s_nop 0
	v_mul_f32_e32 v53, v53, v54
	v_mul_f32_e32 v54, v61, v89
	v_mul_f32_e32 v54, v54, v55
	v_cvt_pk_bf16_f32 v53, v53, v54
	global_store_dwordx4 v[86:87], v[50:53], off
	ds_bpermute_b32 v50, v179, v82 offset:64
	s_nop 0
	v_add_u32_e32 v51, 0x90, v180
	v_mad_i64_i32 v[52:53], s[2:3], v51, s43, v[162:163]
	s_waitcnt lgkmcnt(0)
; __device__ __forceinline__ unsigned cvt_pk_bf16(float lo, float hi) { unsigned r; asm volatile("v_cvt_pk_bf16_f32 %0, %1, %2" : "=v"(r) : "v"(lo), "v"(hi)); return r; }
; __device__ __forceinline__ float silu_mul(float a, float b) { return a * b * __builtin_amdgcn_rcpf(1.0f + __builtin_amdgcn_exp2f(-a * LOG2E)); }
; #define PG8_BAR __builtin_amdgcn_s_barrier()
;     __device__ __forceinline__ void operator()(const f32x4 (&acc)[2][2][4][2], const Unit& u, int wr, int wc, int fr, int fq) const {
;     ...
;             for (int m = 0; m < 4; ++m) { const int row = row0 + ai * HALF + m * 16; const float rs = __shfl(ai ? rsl1 : rsl0, m * 16 + fr); bf16_t* rowp = O + (size_t)row * DFF + col0;
;                 const f32x4 a0 = acc[ai][0][m][0] * rs + ba0, a1 = acc[ai][0][m][1] * rs + ba1, b0 = acc[ai][1][m][0] * rs + bb0, b1 = acc[ai][1][m][1] * rs + bb1;
;                 u32x4 w; w.x = cvt_pk_bf16(silu_mul(a0[0], b0[0]), silu_mul(a0[1], b0[1])); w.y = cvt_pk_bf16(silu_mul(a0[2], b0[2]), silu_mul(a0[3], b0[3]));
;                 w.z = cvt_pk_bf16(silu_mul(a1[0], b1[0]), silu_mul(a1[1], b1[1])); w.w = cvt_pk_bf16(silu_mul(a1[2], b1[2]), silu_mul(a1[3], b1[3]));
;                 *(u32x4*)rowp = w; }
; template <class Epi, class Sched, bool ALIGN_EPI = false, bool SP2 = false>
; __device__ __forceinline__ void gemm_phase(LAS unsigned char* lds, const Gemm g, const Sched& S, const Epi& E) {
;     ...
;         if constexpr (!Epi::AFTER_DRAIN) { E(acc, cur, wr, wc, fr, fq); S.done(cur); }
;         if (!has_next) break;
; #pragma unroll
;         for (int a = 0; a < 2; ++a)
; #pragma unroll
;             for (int b = 0; b < 2; ++b)
; #pragma unroll
;                 for (int m = 0; m < 4; ++m)
; #pragma unroll
;                     for (int n = 0; n < 2; ++n) acc[a][b][m][n] = (f32x4){0.f, 0.f, 0.f, 0.f};
;         cur = nxt; cA = nA; cB = nB; ++ui;
;         if constexpr (ALIGN_EPI) { if (wr == 1) PG8_BAR; }
	v_fma_f32 v46, v46, v50, v78
	v_fma_f32 v47, v47, v50, v79
	v_fma_f32 v38, v38, v50, v70
	v_fma_f32 v39, v39, v50, v71
	v_fma_f32 v54, v36, v50, v68
	v_fma_f32 v55, v37, v50, v69
	v_fma_f32 v36, v34, v50, v66
	v_fma_f32 v37, v35, v50, v67
	v_mul_f32_e32 v35, 0xbfb8aa3b, v46
	v_mul_f32_e32 v34, v46, v38
	v_exp_f32_e32 v35, v35
	v_mul_f32_e32 v38, 0xbfb8aa3b, v47
	v_exp_f32_e32 v38, v38
	v_fma_f32 v48, v48, v50, v80
	v_fma_f32 v49, v49, v50, v81
	v_add_f32_e32 v35, 1.0, v35
	v_rcp_f32_e32 v35, v35
	v_add_f32_e32 v38, 1.0, v38
	v_rcp_f32_e32 v38, v38
	v_fma_f32 v40, v40, v50, v72
	v_fma_f32 v41, v41, v50, v73
	v_mul_f32_e32 v34, v34, v35
	v_mul_f32_e32 v35, v47, v39
	v_mul_f32_e32 v35, v35, v38
	v_mul_f32_e32 v38, 0xbfb8aa3b, v48
	v_exp_f32_e32 v38, v38
	v_mul_f32_e32 v39, 0xbfb8aa3b, v49
	v_exp_f32_e32 v39, v39
	v_cvt_pk_bf16_f32 v34, v34, v35
	v_add_f32_e32 v38, 1.0, v38
	v_rcp_f32_e32 v38, v38
	v_add_f32_e32 v39, 1.0, v39
	v_rcp_f32_e32 v39, v39
	v_mul_f32_e32 v35, v48, v40
	v_mul_f32_e32 v35, v35, v38
	v_mul_f32_e32 v38, v49, v41
	v_fma_f32 v42, v42, v50, v74
	v_fma_f32 v43, v43, v50, v75
	v_mul_f32_e32 v38, v38, v39
	v_cvt_pk_bf16_f32 v35, v35, v38
	v_mul_f32_e32 v38, 0xbfb8aa3b, v42
	v_exp_f32_e32 v38, v38
	v_mul_f32_e32 v36, v42, v36
	v_fma_f32 v44, v44, v50, v76
	v_fma_f32 v45, v45, v50, v77
	v_mul_f32_e32 v37, v43, v37
	v_add_f32_e32 v38, 1.0, v38
	v_rcp_f32_e32 v38, v38
	v_mul_f32_e32 v39, 0xbfb8aa3b, v45
	v_exp_f32_e32 v39, v39
	v_lshl_add_u64 v[52:53], v[52:53], 0, v[164:165]
	v_mul_f32_e32 v36, v36, v38
	v_mul_f32_e32 v38, 0xbfb8aa3b, v43
	v_exp_f32_e32 v38, v38
	v_add_f32_e32 v39, 1.0, v39
	v_rcp_f32_e32 v39, v39
	v_add_f32_e32 v38, 1.0, v38
	v_rcp_f32_e32 v38, v38
	s_nop 0
	v_mul_f32_e32 v37, v37, v38
	v_mul_f32_e32 v38, 0xbfb8aa3b, v44
	v_exp_f32_e32 v38, v38
	v_cvt_pk_bf16_f32 v36, v36, v37
	v_mul_f32_e32 v37, v44, v54
	v_add_f32_e32 v38, 1.0, v38
	v_rcp_f32_e32 v38, v38
	s_nop 0
	v_mul_f32_e32 v37, v37, v38
	v_mul_f32_e32 v38, v45, v55
	v_mul_f32_e32 v38, v38, v39
	v_cvt_pk_bf16_f32 v37, v37, v38
	global_store_dwordx4 v[52:53], v[34:37], off
	ds_bpermute_b32 v34, v179, v82 offset:128
	s_nop 0
	v_add_u32_e32 v35, 0xa0, v180
	v_mad_i64_i32 v[36:37], s[2:3], v35, s43, v[162:163]
	s_waitcnt lgkmcnt(0)
	v_fma_f32 v30, v30, v34, v78
	v_fma_f32 v31, v31, v34, v79
	v_fma_f32 v22, v22, v34, v70
	v_fma_f32 v23, v23, v34, v71
	v_fma_f32 v38, v20, v34, v68
	v_fma_f32 v39, v21, v34, v69
	v_fma_f32 v20, v18, v34, v66
	v_fma_f32 v21, v19, v34, v67
	v_mul_f32_e32 v19, 0xbfb8aa3b, v30
	v_mul_f32_e32 v18, v30, v22
	v_exp_f32_e32 v19, v19
	v_mul_f32_e32 v22, 0xbfb8aa3b, v31
	v_exp_f32_e32 v22, v22
	v_fma_f32 v32, v32, v34, v80
	v_fma_f32 v33, v33, v34, v81
	v_add_f32_e32 v19, 1.0, v19
	v_rcp_f32_e32 v19, v19
	v_add_f32_e32 v22, 1.0, v22
	v_rcp_f32_e32 v22, v22
	v_fma_f32 v24, v24, v34, v72
	v_fma_f32 v25, v25, v34, v73
	v_mul_f32_e32 v18, v18, v19
	v_mul_f32_e32 v19, v31, v23
	v_mul_f32_e32 v19, v19, v22
	v_mul_f32_e32 v22, 0xbfb8aa3b, v32
	v_exp_f32_e32 v22, v22
	v_mul_f32_e32 v23, 0xbfb8aa3b, v33
	v_exp_f32_e32 v23, v23
	v_cvt_pk_bf16_f32 v18, v18, v19
	v_add_f32_e32 v22, 1.0, v22
	v_rcp_f32_e32 v22, v22
	v_add_f32_e32 v23, 1.0, v23
	v_rcp_f32_e32 v23, v23
	v_mul_f32_e32 v19, v32, v24
	v_mul_f32_e32 v19, v19, v22
	v_mul_f32_e32 v22, v33, v25
	v_fma_f32 v26, v26, v34, v74
	v_fma_f32 v27, v27, v34, v75
	v_mul_f32_e32 v22, v22, v23
	v_cvt_pk_bf16_f32 v19, v19, v22
	v_mul_f32_e32 v22, 0xbfb8aa3b, v26
	v_exp_f32_e32 v22, v22
	v_mul_f32_e32 v20, v26, v20
	v_fma_f32 v28, v28, v34, v76
	v_fma_f32 v29, v29, v34, v77
	v_mul_f32_e32 v21, v27, v21
	v_add_f32_e32 v22, 1.0, v22
	v_rcp_f32_e32 v22, v22
	v_mul_f32_e32 v23, 0xbfb8aa3b, v29
	v_exp_f32_e32 v23, v23
	v_lshl_add_u64 v[36:37], v[36:37], 0, v[164:165]
	v_mul_f32_e32 v20, v20, v22
	v_mul_f32_e32 v22, 0xbfb8aa3b, v27
	v_exp_f32_e32 v22, v22
	v_add_f32_e32 v23, 1.0, v23
	v_rcp_f32_e32 v23, v23
	v_add_f32_e32 v22, 1.0, v22
	v_rcp_f32_e32 v22, v22
	s_nop 0
	v_mul_f32_e32 v21, v21, v22
	v_mul_f32_e32 v22, 0xbfb8aa3b, v28
	v_exp_f32_e32 v22, v22
	v_cvt_pk_bf16_f32 v20, v20, v21
	v_mul_f32_e32 v21, v28, v38
	v_add_f32_e32 v22, 1.0, v22
	v_rcp_f32_e32 v22, v22
	s_nop 0
	v_mul_f32_e32 v21, v21, v22
	v_mul_f32_e32 v22, v29, v39
	v_mul_f32_e32 v22, v22, v23
	v_cvt_pk_bf16_f32 v21, v21, v22
	global_store_dwordx4 v[36:37], v[18:21], off
	ds_bpermute_b32 v18, v179, v82 offset:192
	s_nop 0
	v_add_u32_e32 v19, 0xb0, v180
	v_mad_i64_i32 v[20:21], s[2:3], v19, s43, v[162:163]
	s_waitcnt lgkmcnt(0)
	v_fma_f32 v14, v14, v18, v78
	v_fma_f32 v15, v15, v18, v79
	v_fma_f32 v6, v6, v18, v70
	v_fma_f32 v7, v7, v18, v71
	v_fma_f32 v22, v4, v18, v68
	v_fma_f32 v23, v5, v18, v69
	v_fma_f32 v4, v2, v18, v66
	v_fma_f32 v5, v3, v18, v67
	v_mul_f32_e32 v3, 0xbfb8aa3b, v14
	v_mul_f32_e32 v2, v14, v6
	v_exp_f32_e32 v3, v3
	v_mul_f32_e32 v6, 0xbfb8aa3b, v15
	v_exp_f32_e32 v6, v6
	v_fma_f32 v16, v16, v18, v80
	v_fma_f32 v17, v17, v18, v81
	v_add_f32_e32 v3, 1.0, v3
	v_rcp_f32_e32 v3, v3
	v_add_f32_e32 v6, 1.0, v6
	v_rcp_f32_e32 v6, v6
	v_fma_f32 v8, v8, v18, v72
	v_fma_f32 v9, v9, v18, v73
	v_mul_f32_e32 v2, v2, v3
	v_mul_f32_e32 v3, v15, v7
	v_mul_f32_e32 v3, v3, v6
	v_mul_f32_e32 v6, 0xbfb8aa3b, v16
	v_exp_f32_e32 v6, v6
	v_mul_f32_e32 v7, 0xbfb8aa3b, v17
	v_exp_f32_e32 v7, v7
	v_cvt_pk_bf16_f32 v2, v2, v3
	v_add_f32_e32 v6, 1.0, v6
	v_rcp_f32_e32 v6, v6
	v_add_f32_e32 v7, 1.0, v7
	v_rcp_f32_e32 v7, v7
	v_mul_f32_e32 v3, v16, v8
	v_mul_f32_e32 v3, v3, v6
	v_mul_f32_e32 v6, v17, v9
	v_fma_f32 v10, v10, v18, v74
	v_fma_f32 v11, v11, v18, v75
	v_mul_f32_e32 v6, v6, v7
	v_cvt_pk_bf16_f32 v3, v3, v6
	v_mul_f32_e32 v6, 0xbfb8aa3b, v10
	v_exp_f32_e32 v6, v6
	v_mul_f32_e32 v4, v10, v4
	v_fma_f32 v12, v12, v18, v76
	v_fma_f32 v13, v13, v18, v77
	v_mul_f32_e32 v5, v11, v5
	v_add_f32_e32 v6, 1.0, v6
	v_rcp_f32_e32 v6, v6
	v_mul_f32_e32 v7, 0xbfb8aa3b, v13
	v_exp_f32_e32 v7, v7
	v_lshl_add_u64 v[20:21], v[20:21], 0, v[164:165]
	v_mul_f32_e32 v4, v4, v6
	v_mul_f32_e32 v6, 0xbfb8aa3b, v11
	v_exp_f32_e32 v6, v6
	v_add_f32_e32 v7, 1.0, v7
	v_rcp_f32_e32 v7, v7
	s_mov_b64 s[2:3], -1
	v_add_f32_e32 v6, 1.0, v6
	v_rcp_f32_e32 v6, v6
	s_nop 0
	v_mul_f32_e32 v5, v5, v6
	v_mul_f32_e32 v6, 0xbfb8aa3b, v12
	v_exp_f32_e32 v6, v6
	v_cvt_pk_bf16_f32 v4, v4, v5
	v_mul_f32_e32 v5, v12, v22
	v_add_f32_e32 v6, 1.0, v6
	v_rcp_f32_e32 v6, v6
	s_nop 0
	v_mul_f32_e32 v5, v5, v6
	v_mul_f32_e32 v6, v13, v23
	v_mul_f32_e32 v6, v6, v7
	v_cvt_pk_bf16_f32 v5, v5, v6
	global_store_dwordx4 v[20:21], v[2:5], off
	s_cbranch_vccz .LBB0_2912
	s_andn2_b64 vcc, exec, s[4:5]
	s_cbranch_vccnz .LBB0_2911
	s_barrier
	s_branch .LBB0_2911
